# SSD pass 2 loads the bf16 silu(conv(B)) pairs stored by pass 1 instead of recomputing the convolution
# baseline (speedup 1.0000x reference)
; #define LAS __attribute__((address_space(3)))
; DI unsigned pk2(float lo, float hi) { const f32x2 v = {lo, hi}; const hwbf16x2 b = __builtin_convertvector(v, hwbf16x2); return __builtin_bit_cast(unsigned, b); }
; DI void ssd_pass1(LAS unsigned char* lds, const Args& a, const LayerP& P, int unit, int wv) {
;     ...
; #pragma unroll
;     for (int g = 0; g < 2; ++g) {
;         { float o[4][8]; conv_compute<true>(rawX[g], P.ssd_cw + g * 128 + cv * 8, 768, P.ssd_cb + g * 128 + cv * 8, o);
;           const int h = 2 * g + (cv >> 3); const float ae = acs[h * 128 + 127]; float w[4];
; #pragma unroll
;           for (int t = 0; t < 4; ++t) w[t] = __expf(ae - acs[h * 128 + t0 + t]) * dtl[h * 128 + t0 + t];
; #pragma unroll
;           for (int k = 0; k < 8; ++k) { u32x2 v; v.x = pk2(o[0][k] * w[0], o[1][k] * w[1]); v.y = pk2(o[2][k] * w[2], o[3][k] * w[3]); *(LAS u32x2*)(XT + (h * 64 + (cv & 7) * 8 + k) * PT + t0) = v; } }
.LBB0_992:
	v_lshlrev_b32_e32 v0, 3, v165
	v_and_b32_e32 v169, 56, v0
	v_lshlrev_b32_e32 v172, 1, v167
	s_add_i32 s2, 0, 0x11000
	v_lshlrev_b32_e32 v0, 2, v118
	v_add_u32_e32 v168, s2, v172
	v_lshl_add_u64 v[156:157], s[42:43], 0, v[0:1]
	s_movk_i32 s2, 0x1000
	v_add_co_u32_e32 v158, vcc, s2, v156
	s_mov_b64 s[2:3], 0x2400
	s_nop 0
	v_addc_co_u32_e32 v159, vcc, 0, v157, vcc
	v_lshl_add_u64 v[126:127], v[156:157], 0, s[2:3]
	s_movk_i32 s2, 0x2000
	v_add_co_u32_e32 v154, vcc, s2, v156
	v_lshl_add_u64 v[122:123], v[156:157], 0, s[64:65]
	s_nop 0
	v_addc_co_u32_e32 v155, vcc, 0, v157, vcc
	s_waitcnt lgkmcnt(0)
	s_barrier
	v_mbcnt_lo_u32_b32 v220, -1, 0
	v_mbcnt_hi_u32_b32 v220, -1, v220
	v_lshl_or_b32 v220, s77, 6, v220
	v_lshlrev_b32_e32 v220, 6, v220
	s_lshl_b32 s32, s34, 16
	v_add_u32_e32 v220, s32, v220
	v_add_u32_e32 v221, 0x8000, v220
	s_add_u32 s92, s38, 0x1b100000
	s_addc_u32 s93, s39, 0
	global_load_dwordx4 v[114:117], v0, s[42:43] offset:16
	global_load_dwordx4 v[134:137], v0, s[42:43]
	global_load_dwordx4 v[118:121], v0, s[42:43] offset:3088
	global_load_dwordx4 v[138:141], v0, s[42:43] offset:3072
	global_load_dwordx4 v[142:145], v[158:159], off offset:2048
	s_nop 0
	global_load_dwordx4 v[122:125], v[122:123], off offset:16
	s_nop 0
	global_load_dwordx4 v[146:149], v[154:155], off offset:1024
	s_nop 0
	global_load_dwordx4 v[126:129], v[126:127], off offset:16
	s_nop 0
	global_load_dwordx4 v[130:133], v0, s[46:47] offset:16
	global_load_dwordx4 v[150:153], v0, s[46:47]
	v_lshrrev_b32_e32 v170, 3, v166
	v_readlane_b32 s3, v254, 12
	v_lshlrev_b32_e32 v171, 2, v167
	s_waitcnt vmcnt(10)
	v_lshlrev_b32_e32 v181, 16, v94
	v_lshl_add_u32 v160, v170, 9, s3
	ds_read_b32 v173, v160 offset:508
	v_add_u32_e32 v160, v160, v171
	ds_read_b128 v[160:163], v160
	v_lshlrev_b32_e32 v180, 16, v98
	v_lshlrev_b32_e32 v183, 16, v106
	v_mov_b32_e32 v182, v181
	v_lshl_add_u32 v174, v170, 7, v167
	s_waitcnt lgkmcnt(0)
	v_sub_f32_e32 v160, v173, v160
	v_mul_f32_e32 v160, 0x3fb8aa3b, v160
	v_exp_f32_e32 v178, v160
	v_sub_f32_e32 v160, v173, v161
	v_mul_f32_e32 v160, 0x3fb8aa3b, v160
	s_add_i32 s2, 0, 0x22800
	v_exp_f32_e32 v179, v160
	v_sub_f32_e32 v160, v173, v162
	v_sub_f32_e32 v161, v173, v163
	v_lshlrev_b32_e32 v163, 16, v102
	v_mov_b32_e32 v162, v183
	v_lshl_add_u32 v186, v174, 2, s2
	v_lshlrev_b32_e32 v175, 16, v110
	v_mov_b32_e32 v174, v163
	v_mul_f32_e32 v160, 0x3fb8aa3b, v160
	v_mul_f32_e32 v161, 0x3fb8aa3b, v161
	v_exp_f32_e32 v160, v160
	v_exp_f32_e32 v161, v161
	v_lshl_or_b32 v173, v170, 6, v169
	v_mad_u32_u24 v173, v173, s56, v168
	s_mov_b64 s[12:13], 0x400
	s_waitcnt vmcnt(0)
	v_pk_fma_f32 v[176:177], v[134:135], v[180:181], v[150:151] op_sel_hi:[0,1,0]
	v_pk_fma_f32 v[176:177], v[138:139], v[182:183], v[176:177] op_sel_hi:[0,1,1]
	v_pk_fma_f32 v[162:163], v[142:143], v[162:163], v[176:177] op_sel_hi:[0,1,1]
	v_pk_fma_f32 v[162:163], v[146:147], v[174:175], v[162:163] op_sel_hi:[0,1,1]
	v_mul_f32_e32 v174, 0xbfb8aa3b, v162
	v_mul_f32_e32 v175, 0xbfb8aa3b, v163
	v_exp_f32_e32 v174, v174
	v_exp_f32_e32 v175, v175
	v_add_f32_e32 v174, 1.0, v174
	v_add_f32_e32 v175, 1.0, v175
	v_rcp_f32_e32 v174, v174
	v_rcp_f32_e32 v175, v175
	s_nop 0
	v_pk_mul_f32 v[184:185], v[162:163], v[174:175]
	ds_read_b128 v[174:177], v186
	s_waitcnt lgkmcnt(0)
	v_pk_mul_f32 v[160:161], v[176:177], v[160:161]
	v_lshlrev_b32_e32 v177, 16, v74
	v_lshlrev_b32_e32 v176, 16, v78
	v_pk_fma_f32 v[186:187], v[134:135], v[176:177], v[150:151] op_sel_hi:[0,1,0]
	v_pk_mul_f32 v[162:163], v[174:175], v[178:179]
	v_pk_mov_b32 v[174:175], v[176:177], v[180:181] op_sel:[1,0]
	v_and_b32_e32 v179, 0xffff0000, v106
	v_pk_fma_f32 v[174:175], v[138:139], v[174:175], v[186:187] op_sel_hi:[0,1,1]
	v_pk_fma_f32 v[174:175], v[142:143], v[180:181], v[174:175] op_sel_hi:[0,1,1]
	v_pk_fma_f32 v[174:175], v[146:147], v[182:183], v[174:175] op_sel_hi:[0,1,1]
	v_mul_f32_e32 v176, 0xbfb8aa3b, v174
	v_mul_f32_e32 v177, 0xbfb8aa3b, v175
	v_exp_f32_e32 v176, v176
	v_exp_f32_e32 v177, v177
	v_and_b32_e32 v181, 0xffff0000, v102
	v_mov_b32_e32 v180, v179
	v_add_f32_e32 v176, 1.0, v176
	v_add_f32_e32 v177, 1.0, v177
	v_rcp_f32_e32 v176, v176
	v_rcp_f32_e32 v177, v177
	v_and_b32_e32 v183, 0xffff0000, v110
	v_mov_b32_e32 v182, v181
	v_pk_mul_f32 v[174:175], v[174:175], v[176:177]
	s_nop 0
	v_pk_mul_f32 v[174:175], v[162:163], v[174:175]
	v_pk_mul_f32 v[176:177], v[184:185], v[160:161]
	v_cvt_pk_bf16_f32 v174, v174, v175
	v_cvt_pk_bf16_f32 v175, v176, v177
	v_and_b32_e32 v177, 0xffff0000, v94
	v_and_b32_e32 v176, 0xffff0000, v98
	v_mov_b32_e32 v178, v177
	v_pk_fma_f32 v[184:185], v[134:135], v[176:177], v[150:151] op_sel:[1,0,1]
	s_nop 0
	v_pk_fma_f32 v[184:185], v[138:139], v[178:179], v[184:185] op_sel:[1,0,0]
	s_nop 0
	v_pk_fma_f32 v[180:181], v[142:143], v[180:181], v[184:185] op_sel:[1,0,0]
	s_nop 0
	v_pk_fma_f32 v[180:181], v[146:147], v[182:183], v[180:181] op_sel:[1,0,0]
	s_nop 0
	v_mul_f32_e32 v94, 0xbfb8aa3b, v180
	v_exp_f32_e32 v94, v94
	s_nop 0
	v_add_f32_e32 v94, 1.0, v94
	v_rcp_f32_e32 v182, v94
	v_mul_f32_e32 v94, 0xbfb8aa3b, v181
	v_exp_f32_e32 v94, v94
	s_nop 0
	v_add_f32_e32 v94, 1.0, v94
	v_rcp_f32_e32 v183, v94
	v_and_b32_e32 v94, 0xffff0000, v99
	v_pk_mul_f32 v[180:181], v[180:181], v[182:183]
	v_and_b32_e32 v183, 0xffff0000, v74
	v_and_b32_e32 v182, 0xffff0000, v78
	v_pk_fma_f32 v[134:135], v[134:135], v[182:183], v[150:151] op_sel:[1,0,1]
	v_pk_mov_b32 v[150:151], v[182:183], v[176:177] op_sel:[1,0]
	v_mov_b32_e32 v78, v153
	v_pk_fma_f32 v[134:135], v[138:139], v[150:151], v[134:135] op_sel:[1,0,0]
	s_nop 0
	v_pk_fma_f32 v[134:135], v[142:143], v[176:177], v[134:135] op_sel:[1,0,0]
; #define LAS __attribute__((address_space(3)))
; DI unsigned pk2(float lo, float hi) { const f32x2 v = {lo, hi}; const hwbf16x2 b = __builtin_convertvector(v, hwbf16x2); return __builtin_bit_cast(unsigned, b); }
; DI void ssd_pass1(LAS unsigned char* lds, const Args& a, const LayerP& P, int unit, int wv) {
;     ...
;         { float o[4][8]; conv_compute<true>(rawX[g], P.ssd_cw + g * 128 + cv * 8, 768, P.ssd_cb + g * 128 + cv * 8, o);
;           const int h = 2 * g + (cv >> 3); const float ae = acs[h * 128 + 127]; float w[4];
; #pragma unroll
;           for (int t = 0; t < 4; ++t) w[t] = __expf(ae - acs[h * 128 + t0 + t]) * dtl[h * 128 + t0 + t];
; #pragma unroll
;           for (int k = 0; k < 8; ++k) { u32x2 v; v.x = pk2(o[0][k] * w[0], o[1][k] * w[1]); v.y = pk2(o[2][k] * w[2], o[3][k] * w[3]); *(LAS u32x2*)(XT + (h * 64 + (cv & 7) * 8 + k) * PT + t0) = v; } }
	v_lshlrev_b32_e32 v143, 16, v103
	v_pk_fma_f32 v[134:135], v[146:147], v[178:179], v[134:135] op_sel:[1,0,0]
	v_lshlrev_b32_e32 v147, 16, v111
	v_mul_f32_e32 v74, 0xbfb8aa3b, v134
	v_exp_f32_e32 v74, v74
	v_mov_b32_e32 v146, v143
	v_and_b32_e32 v103, 0xffff0000, v103
	v_mov_b32_e32 v106, v103
	v_add_f32_e32 v74, 1.0, v74
	v_rcp_f32_e32 v138, v74
	v_mul_f32_e32 v74, 0xbfb8aa3b, v135
	v_exp_f32_e32 v74, v74
	s_nop 0
	v_add_f32_e32 v74, 1.0, v74
	v_rcp_f32_e32 v139, v74
	s_nop 0
	v_pk_mul_f32 v[134:135], v[134:135], v[138:139]
	s_nop 0
	v_pk_mul_f32 v[134:135], v[162:163], v[134:135]
	v_pk_mul_f32 v[138:139], v[180:181], v[160:161]
	v_cvt_pk_bf16_f32 v134, v134, v135
	v_cvt_pk_bf16_f32 v135, v138, v139
	ds_write2_b64 v173, v[174:175], v[134:135] offset1:34
	v_lshlrev_b32_e32 v134, 16, v99
	v_lshlrev_b32_e32 v135, 16, v95
	v_lshlrev_b32_e32 v139, 16, v107
	v_mov_b32_e32 v138, v135
	v_pk_fma_f32 v[150:151], v[136:137], v[134:135], v[152:153] op_sel_hi:[0,1,0]
	v_mov_b32_e32 v142, v139
	v_pk_fma_f32 v[150:151], v[140:141], v[138:139], v[150:151] op_sel_hi:[0,1,1]
	v_pk_fma_f32 v[142:143], v[144:145], v[142:143], v[150:151] op_sel_hi:[0,1,1]
	v_pk_fma_f32 v[142:143], v[148:149], v[146:147], v[142:143] op_sel_hi:[0,1,1]
	v_mul_f32_e32 v74, 0xbfb8aa3b, v142
	v_exp_f32_e32 v74, v74
	v_and_b32_e32 v95, 0xffff0000, v95
	v_and_b32_e32 v99, 0xffff0000, v107
	v_mov_b32_e32 v98, v95
	v_add_f32_e32 v74, 1.0, v74
	v_rcp_f32_e32 v146, v74
	v_mul_f32_e32 v74, 0xbfb8aa3b, v143
	v_exp_f32_e32 v74, v74
	v_and_b32_e32 v107, 0xffff0000, v111
	v_mov_b32_e32 v102, v99
	v_add_f32_e32 v74, 1.0, v74
	v_rcp_f32_e32 v147, v74
	s_nop 0
	v_pk_mul_f32 v[142:143], v[142:143], v[146:147]
	v_lshlrev_b32_e32 v146, 16, v79
	v_lshlrev_b32_e32 v147, 16, v75
	v_pk_fma_f32 v[150:151], v[136:137], v[146:147], v[152:153] op_sel_hi:[0,1,0]
	v_pk_mov_b32 v[146:147], v[146:147], v[134:135] op_sel:[1,0]
	v_mov_b32_e32 v136, v141
	v_pk_fma_f32 v[146:147], v[140:141], v[146:147], v[150:151] op_sel_hi:[0,1,1]
	v_pk_fma_f32 v[134:135], v[144:145], v[134:135], v[146:147] op_sel_hi:[0,1,1]
	v_pk_fma_f32 v[134:135], v[148:149], v[138:139], v[134:135] op_sel_hi:[0,1,1]
	v_mul_f32_e32 v74, 0xbfb8aa3b, v134
	v_exp_f32_e32 v74, v74
	s_nop 0
	v_add_f32_e32 v74, 1.0, v74
	v_rcp_f32_e32 v138, v74
	v_mul_f32_e32 v74, 0xbfb8aa3b, v135
	v_exp_f32_e32 v74, v74
	s_nop 0
	v_add_f32_e32 v74, 1.0, v74
	v_rcp_f32_e32 v139, v74
	v_mov_b32_e32 v74, v137
	v_pk_fma_f32 v[110:111], v[74:75], v[94:95], v[78:79] op_sel_hi:[0,1,0]
	v_pk_fma_f32 v[110:111], v[136:137], v[98:99], v[110:111] op_sel_hi:[0,1,1]
	v_pk_mul_f32 v[134:135], v[134:135], v[138:139]
	v_pk_mul_f32 v[138:139], v[142:143], v[160:161]
	v_pk_mul_f32 v[134:135], v[162:163], v[134:135]
	s_nop 0
	v_cvt_pk_bf16_f32 v134, v134, v135
	v_cvt_pk_bf16_f32 v135, v138, v139
	v_mov_b32_e32 v138, v145
	v_pk_fma_f32 v[102:103], v[138:139], v[102:103], v[110:111] op_sel_hi:[0,1,1]
	v_mov_b32_e32 v110, v149
	v_pk_fma_f32 v[102:103], v[110:111], v[106:107], v[102:103] op_sel_hi:[0,1,1]
	v_mul_f32_e32 v106, 0xbfb8aa3b, v102
	v_mul_f32_e32 v107, 0xbfb8aa3b, v103
	v_exp_f32_e32 v106, v106
	v_exp_f32_e32 v107, v107
	v_add_f32_e32 v106, 1.0, v106
	v_add_f32_e32 v107, 1.0, v107
	v_rcp_f32_e32 v106, v106
	v_rcp_f32_e32 v107, v107
	s_nop 0
	v_pk_mul_f32 v[102:103], v[102:103], v[106:107]
	v_and_b32_e32 v107, 0xffff0000, v75
	v_and_b32_e32 v106, 0xffff0000, v79
	v_pk_fma_f32 v[74:75], v[74:75], v[106:107], v[78:79] op_sel_hi:[0,1,0]
	v_pk_mov_b32 v[78:79], v[106:107], v[94:95] op_sel:[1,0]
	s_nop 0
	v_pk_fma_f32 v[74:75], v[136:137], v[78:79], v[74:75] op_sel_hi:[0,1,1]
	v_pk_fma_f32 v[74:75], v[138:139], v[94:95], v[74:75] op_sel_hi:[0,1,1]
	v_pk_fma_f32 v[74:75], v[110:111], v[98:99], v[74:75] op_sel_hi:[0,1,1]
	v_mul_f32_e32 v78, 0xbfb8aa3b, v74
	v_mul_f32_e32 v79, 0xbfb8aa3b, v75
	v_exp_f32_e32 v78, v78
	v_exp_f32_e32 v79, v79
	v_lshlrev_b32_e32 v95, 16, v104
	v_lshlrev_b32_e32 v99, 16, v112
	v_add_f32_e32 v78, 1.0, v78
	v_add_f32_e32 v79, 1.0, v79
	v_rcp_f32_e32 v78, v78
	v_rcp_f32_e32 v79, v79
	v_mov_b32_e32 v98, v95
	v_and_b32_e32 v139, 0xffff0000, v62
	v_and_b32_e32 v138, 0xffff0000, v58
	v_pk_mul_f32 v[74:75], v[74:75], v[78:79]
	v_pk_mul_f32 v[78:79], v[102:103], v[160:161]
	v_pk_mul_f32 v[74:75], v[162:163], v[74:75]
	s_nop 0
	v_cvt_pk_bf16_f32 v74, v74, v75
	v_cvt_pk_bf16_f32 v75, v78, v79
	ds_write2_b64 v173, v[134:135], v[74:75] offset0:68 offset1:102
	v_lshlrev_b32_e32 v75, 16, v96
	v_lshlrev_b32_e32 v74, 16, v100
	v_lshlrev_b32_e32 v79, 16, v108
	v_mov_b32_e32 v78, v75
	v_pk_fma_f32 v[102:103], v[114:115], v[74:75], v[130:131] op_sel_hi:[0,1,0]
	v_mov_b32_e32 v94, v79
	v_pk_fma_f32 v[102:103], v[118:119], v[78:79], v[102:103] op_sel_hi:[0,1,1]
	v_pk_fma_f32 v[94:95], v[122:123], v[94:95], v[102:103] op_sel_hi:[0,1,1]
	v_pk_fma_f32 v[94:95], v[126:127], v[98:99], v[94:95] op_sel_hi:[0,1,1]
	v_mul_f32_e32 v98, 0xbfb8aa3b, v94
	v_mul_f32_e32 v99, 0xbfb8aa3b, v95
	v_exp_f32_e32 v98, v98
	v_exp_f32_e32 v99, v99
	v_lshlrev_b32_e32 v135, 16, v86
	v_add_f32_e32 v98, 1.0, v98
	v_add_f32_e32 v99, 1.0, v99
	v_rcp_f32_e32 v98, v98
	v_rcp_f32_e32 v99, v99
	s_nop 0
	v_pk_mul_f32 v[94:95], v[94:95], v[98:99]
	v_lshlrev_b32_e32 v99, 16, v76
	v_lshlrev_b32_e32 v98, 16, v80
	v_pk_fma_f32 v[102:103], v[114:115], v[98:99], v[130:131] op_sel_hi:[0,1,0]
	v_pk_mov_b32 v[98:99], v[98:99], v[74:75] op_sel:[1,0]
	s_nop 0
	v_pk_fma_f32 v[98:99], v[118:119], v[98:99], v[102:103] op_sel_hi:[0,1,1]
	v_pk_fma_f32 v[74:75], v[122:123], v[74:75], v[98:99] op_sel_hi:[0,1,1]
	v_pk_fma_f32 v[74:75], v[126:127], v[78:79], v[74:75] op_sel_hi:[0,1,1]
	v_mul_f32_e32 v78, 0xbfb8aa3b, v74
; #define LAS __attribute__((address_space(3)))
; DI unsigned pk2(float lo, float hi) { const f32x2 v = {lo, hi}; const hwbf16x2 b = __builtin_convertvector(v, hwbf16x2); return __builtin_bit_cast(unsigned, b); }
; DI float silu_f(float x) { return x * __builtin_amdgcn_rcpf(1.0f + __expf(-x)); }
; template <bool SILU>
; DI void conv_compute(const u32x4 (&raw)[7], const float* w, int C, const float* bias, float (&out)[4][8]) {
;     float wv[4][8], bv[8], x[7][8];
; #pragma unroll
;     for (int j = 0; j < 4; ++j) { const f32x4 a = *(const f32x4*)(w + (size_t)j * C), b = *(const f32x4*)(w + (size_t)j * C + 4);
;         wv[j][0] = a[0]; wv[j][1] = a[1]; wv[j][2] = a[2]; wv[j][3] = a[3]; wv[j][4] = b[0]; wv[j][5] = b[1]; wv[j][6] = b[2]; wv[j][7] = b[3]; }
;     { const f32x4 a = *(const f32x4*)bias, b = *(const f32x4*)(bias + 4); bv[0] = a[0]; bv[1] = a[1]; bv[2] = a[2]; bv[3] = a[3]; bv[4] = b[0]; bv[5] = b[1]; bv[6] = b[2]; bv[7] = b[3]; }
; #pragma unroll
;     for (int i = 0; i < 7; ++i) unpack8(raw[i], x[i]);
; #pragma unroll
;     for (int t = 0; t < 4; ++t)
; #pragma unroll
;         for (int c = 0; c < 8; ++c) { float v = bv[c] + wv[0][c] * x[t][c] + wv[1][c] * x[t + 1][c] + wv[2][c] * x[t + 2][c] + wv[3][c] * x[t + 3][c]; out[t][c] = SILU ? silu_f(v) : v; }
; }
; DI void ssd_pass1(LAS unsigned char* lds, const Args& a, const LayerP& P, int unit, int wv) {
;     ...
;         { float o[4][8]; conv_compute<true>(rawX[g], P.ssd_cw + g * 128 + cv * 8, 768, P.ssd_cb + g * 128 + cv * 8, o);
;           const int h = 2 * g + (cv >> 3); const float ae = acs[h * 128 + 127]; float w[4];
; #pragma unroll
;           for (int t = 0; t < 4; ++t) w[t] = __expf(ae - acs[h * 128 + t0 + t]) * dtl[h * 128 + t0 + t];
; #pragma unroll
;           for (int k = 0; k < 8; ++k) { u32x2 v; v.x = pk2(o[0][k] * w[0], o[1][k] * w[1]); v.y = pk2(o[2][k] * w[2], o[3][k] * w[3]); *(LAS u32x2*)(XT + (h * 64 + (cv & 7) * 8 + k) * PT + t0) = v; } }
;         { float o[4][8]; conv_compute<true>(rawB[g], P.ssd_cw + 256 + g * 128 + cv * 8, 768, P.ssd_cb + 256 + g * 128 + cv * 8, o);
	v_mul_f32_e32 v79, 0xbfb8aa3b, v75
	v_exp_f32_e32 v78, v78
	v_exp_f32_e32 v79, v79
	v_and_b32_e32 v99, 0xffff0000, v104
	v_and_b32_e32 v103, 0xffff0000, v112
	v_add_f32_e32 v78, 1.0, v78
	v_add_f32_e32 v79, 1.0, v79
	v_rcp_f32_e32 v78, v78
	v_rcp_f32_e32 v79, v79
	v_mov_b32_e32 v102, v99
	v_mov_b32_e32 v104, v125
	v_pk_mul_f32 v[74:75], v[74:75], v[78:79]
	s_nop 0
	v_pk_mul_f32 v[74:75], v[162:163], v[74:75]
	v_pk_mul_f32 v[78:79], v[94:95], v[160:161]
	v_cvt_pk_bf16_f32 v74, v74, v75
	v_cvt_pk_bf16_f32 v75, v78, v79
	v_and_b32_e32 v79, 0xffff0000, v96
	v_and_b32_e32 v78, 0xffff0000, v100
	v_and_b32_e32 v95, 0xffff0000, v108
	v_mov_b32_e32 v94, v79
	v_pk_fma_f32 v[106:107], v[114:115], v[78:79], v[130:131] op_sel:[1,0,1]
	v_mov_b32_e32 v98, v95
	v_pk_fma_f32 v[106:107], v[118:119], v[94:95], v[106:107] op_sel:[1,0,0]
	v_lshlrev_b32_e32 v108, 16, v66
	v_pk_fma_f32 v[98:99], v[122:123], v[98:99], v[106:107] op_sel:[1,0,0]
	s_nop 0
	v_pk_fma_f32 v[98:99], v[126:127], v[102:103], v[98:99] op_sel:[1,0,0]
	s_nop 0
	v_mul_f32_e32 v96, 0xbfb8aa3b, v98
	v_exp_f32_e32 v96, v96
	s_nop 0
	v_add_f32_e32 v96, 1.0, v96
	v_rcp_f32_e32 v102, v96
	v_mul_f32_e32 v96, 0xbfb8aa3b, v99
	v_exp_f32_e32 v96, v96
	s_nop 0
	v_add_f32_e32 v96, 1.0, v96
	v_rcp_f32_e32 v103, v96
	s_nop 0
	v_pk_mul_f32 v[98:99], v[98:99], v[102:103]
	v_and_b32_e32 v103, 0xffff0000, v76
	v_and_b32_e32 v102, 0xffff0000, v80
	v_pk_fma_f32 v[106:107], v[114:115], v[102:103], v[130:131] op_sel:[1,0,1]
	v_pk_mov_b32 v[102:103], v[102:103], v[78:79] op_sel:[1,0]
	v_mov_b32_e32 v80, v133
	v_pk_fma_f32 v[102:103], v[118:119], v[102:103], v[106:107] op_sel:[1,0,0]
	v_lshlrev_b32_e32 v107, 16, v62
	v_pk_fma_f32 v[78:79], v[122:123], v[78:79], v[102:103] op_sel:[1,0,0]
	v_lshlrev_b32_e32 v106, 16, v58
	v_pk_fma_f32 v[78:79], v[126:127], v[94:95], v[78:79] op_sel:[1,0,0]
	v_lshlrev_b32_e32 v131, 16, v70
	v_mul_f32_e32 v76, 0xbfb8aa3b, v78
	v_exp_f32_e32 v76, v76
	v_and_b32_e32 v62, 0xffff0000, v59
	v_add_f32_e32 v76, 1.0, v76
	v_rcp_f32_e32 v94, v76
	v_mul_f32_e32 v76, 0xbfb8aa3b, v79
	v_exp_f32_e32 v76, v76
	s_nop 0
	v_add_f32_e32 v76, 1.0, v76
	v_rcp_f32_e32 v95, v76
	s_nop 0
	v_pk_mul_f32 v[78:79], v[78:79], v[94:95]
	s_nop 0
	v_pk_mul_f32 v[78:79], v[162:163], v[78:79]
	v_pk_mul_f32 v[94:95], v[98:99], v[160:161]
	v_cvt_pk_bf16_f32 v78, v78, v79
	v_cvt_pk_bf16_f32 v79, v94, v95
	ds_write2_b64 v173, v[74:75], v[78:79] offset0:136 offset1:170
	v_lshlrev_b32_e32 v74, 16, v101
	v_lshlrev_b32_e32 v75, 16, v97
	v_lshlrev_b32_e32 v79, 16, v109
	v_mov_b32_e32 v78, v75
	v_pk_fma_f32 v[102:103], v[116:117], v[74:75], v[132:133] op_sel_hi:[0,1,0]
	v_lshlrev_b32_e32 v95, 16, v105
	v_mov_b32_e32 v94, v79
	v_pk_fma_f32 v[102:103], v[120:121], v[78:79], v[102:103] op_sel_hi:[0,1,1]
	v_lshlrev_b32_e32 v99, 16, v113
	v_mov_b32_e32 v98, v95
	v_pk_fma_f32 v[94:95], v[124:125], v[94:95], v[102:103] op_sel_hi:[0,1,1]
	v_pk_fma_f32 v[94:95], v[128:129], v[98:99], v[94:95] op_sel_hi:[0,1,1]
	v_mul_f32_e32 v76, 0xbfb8aa3b, v94
	v_exp_f32_e32 v76, v76
	s_nop 0
	v_add_f32_e32 v76, 1.0, v76
	v_rcp_f32_e32 v98, v76
	v_mul_f32_e32 v76, 0xbfb8aa3b, v95
	v_exp_f32_e32 v76, v76
	s_nop 0
	v_add_f32_e32 v76, 1.0, v76
	v_rcp_f32_e32 v99, v76
	s_nop 0
	v_pk_mul_f32 v[94:95], v[94:95], v[98:99]
	v_lshlrev_b32_e32 v98, 16, v81
	v_lshlrev_b32_e32 v99, 16, v77
	v_pk_fma_f32 v[102:103], v[116:117], v[98:99], v[132:133] op_sel_hi:[0,1,0]
	v_pk_mov_b32 v[98:99], v[98:99], v[74:75] op_sel:[1,0]
	v_lshlrev_b32_e32 v133, 16, v90
	v_pk_fma_f32 v[98:99], v[120:121], v[98:99], v[102:103] op_sel_hi:[0,1,1]
	v_pk_fma_f32 v[74:75], v[124:125], v[74:75], v[98:99] op_sel_hi:[0,1,1]
	v_pk_fma_f32 v[74:75], v[128:129], v[78:79], v[74:75] op_sel_hi:[0,1,1]
	v_mul_f32_e32 v76, 0xbfb8aa3b, v74
	v_exp_f32_e32 v76, v76
	v_mov_b32_e32 v102, v121
	v_and_b32_e32 v99, 0xffff0000, v113
	v_mov_b32_e32 v132, v131
	v_add_f32_e32 v76, 1.0, v76
	v_rcp_f32_e32 v78, v76
	v_mul_f32_e32 v76, 0xbfb8aa3b, v75
	v_exp_f32_e32 v76, v76
	v_mov_b32_e32 v134, v133
	v_add_f32_e32 v76, 1.0, v76
	v_rcp_f32_e32 v79, v76
	v_mov_b32_e32 v76, v117
	v_pk_mul_f32 v[74:75], v[74:75], v[78:79]
	s_nop 0
	v_pk_mul_f32 v[74:75], v[162:163], v[74:75]
	v_pk_mul_f32 v[78:79], v[94:95], v[160:161]
	v_cvt_pk_bf16_f32 v74, v74, v75
	v_cvt_pk_bf16_f32 v75, v78, v79
	v_and_b32_e32 v79, 0xffff0000, v97
	v_and_b32_e32 v78, 0xffff0000, v101
	v_and_b32_e32 v95, 0xffff0000, v109
	v_mov_b32_e32 v94, v79
	v_pk_fma_f32 v[100:101], v[76:77], v[78:79], v[80:81] op_sel_hi:[0,1,0]
	v_and_b32_e32 v97, 0xffff0000, v105
	v_mov_b32_e32 v96, v95
	v_pk_fma_f32 v[100:101], v[102:103], v[94:95], v[100:101] op_sel_hi:[0,1,1]
	v_mov_b32_e32 v98, v97
	v_pk_fma_f32 v[96:97], v[104:105], v[96:97], v[100:101] op_sel_hi:[0,1,1]
	v_mov_b32_e32 v100, v129
	v_pk_fma_f32 v[96:97], v[100:101], v[98:99], v[96:97] op_sel_hi:[0,1,1]
	v_mul_f32_e32 v98, 0xbfb8aa3b, v96
	v_mul_f32_e32 v99, 0xbfb8aa3b, v97
	v_exp_f32_e32 v98, v98
	v_exp_f32_e32 v99, v99
	v_lshlrev_b32_e32 v109, 16, v82
	v_mov_b32_e32 v130, v109
	v_add_f32_e32 v98, 1.0, v98
	v_add_f32_e32 v99, 1.0, v99
	v_rcp_f32_e32 v98, v98
	v_rcp_f32_e32 v99, v99
	s_nop 0
	v_pk_mul_f32 v[96:97], v[96:97], v[98:99]
	v_and_b32_e32 v99, 0xffff0000, v77
	v_and_b32_e32 v98, 0xffff0000, v81
	v_pk_fma_f32 v[76:77], v[76:77], v[98:99], v[80:81] op_sel_hi:[0,1,0]
	v_pk_mov_b32 v[80:81], v[98:99], v[78:79] op_sel:[1,0]
	s_nop 0
	v_pk_fma_f32 v[76:77], v[102:103], v[80:81], v[76:77] op_sel_hi:[0,1,1]
	v_pk_fma_f32 v[76:77], v[104:105], v[78:79], v[76:77] op_sel_hi:[0,1,1]
	v_pk_fma_f32 v[76:77], v[100:101], v[94:95], v[76:77] op_sel_hi:[0,1,1]
	v_mul_f32_e32 v78, 0xbfb8aa3b, v76
	v_mul_f32_e32 v79, 0xbfb8aa3b, v77
	v_exp_f32_e32 v78, v78
	v_exp_f32_e32 v79, v79
	v_lshl_add_u64 v[94:95], v[156:157], 0, s[12:13]
	s_mov_b64 s[12:13], 0x1c00
	v_add_f32_e32 v78, 1.0, v78
	v_add_f32_e32 v79, 1.0, v79
	v_rcp_f32_e32 v78, v78
	v_rcp_f32_e32 v79, v79
	s_nop 0
	v_pk_mul_f32 v[76:77], v[76:77], v[78:79]
	s_nop 0
	v_pk_mul_f32 v[76:77], v[162:163], v[76:77]
	v_pk_mul_f32 v[78:79], v[96:97], v[160:161]
	v_cvt_pk_bf16_f32 v76, v76, v77
	v_cvt_pk_bf16_f32 v77, v78, v79
	ds_write2_b64 v173, v[74:75], v[76:77] offset0:204 offset1:238
	global_load_dwordx4 v[78:81], v0, s[42:43] offset:1040
	global_load_dwordx4 v[110:113], v0, s[42:43] offset:1024
	global_load_dwordx4 v[74:77], v[94:95], off offset:3088
	global_load_dwordx4 v[114:117], v[94:95], off offset:3072
	v_lshl_add_u64 v[94:95], v[156:157], 0, s[12:13]
	s_mov_b64 s[12:13], 0x2800
	v_lshl_add_u64 v[98:99], v[156:157], 0, s[12:13]
	global_load_dwordx4 v[118:121], v[158:159], off offset:3072
	s_nop 0
	global_load_dwordx4 v[94:97], v[94:95], off offset:16
	s_nop 0
	global_load_dwordx4 v[122:125], v[154:155], off offset:2048
	s_nop 0
	global_load_dwordx4 v[98:101], v[98:99], off offset:16
	s_nop 0
	global_load_dwordx4 v[102:105], v0, s[46:47] offset:1040
	global_load_dwordx4 v[126:129], v0, s[46:47] offset:1024
	s_mov_b64 s[12:13], 0x1a00
	s_waitcnt vmcnt(0)
; #define LAS __attribute__((address_space(3)))
; DI unsigned pk2(float lo, float hi) { const f32x2 v = {lo, hi}; const hwbf16x2 b = __builtin_convertvector(v, hwbf16x2); return __builtin_bit_cast(unsigned, b); }
; DI float silu_f(float x) { return x * __builtin_amdgcn_rcpf(1.0f + __expf(-x)); }
; template <bool SILU>
; DI void conv_compute(const u32x4 (&raw)[7], const float* w, int C, const float* bias, float (&out)[4][8]) {
;     float wv[4][8], bv[8], x[7][8];
; #pragma unroll
;     for (int j = 0; j < 4; ++j) { const f32x4 a = *(const f32x4*)(w + (size_t)j * C), b = *(const f32x4*)(w + (size_t)j * C + 4);
;         wv[j][0] = a[0]; wv[j][1] = a[1]; wv[j][2] = a[2]; wv[j][3] = a[3]; wv[j][4] = b[0]; wv[j][5] = b[1]; wv[j][6] = b[2]; wv[j][7] = b[3]; }
;     { const f32x4 a = *(const f32x4*)bias, b = *(const f32x4*)(bias + 4); bv[0] = a[0]; bv[1] = a[1]; bv[2] = a[2]; bv[3] = a[3]; bv[4] = b[0]; bv[5] = b[1]; bv[6] = b[2]; bv[7] = b[3]; }
; #pragma unroll
;     for (int i = 0; i < 7; ++i) unpack8(raw[i], x[i]);
; #pragma unroll
;     for (int t = 0; t < 4; ++t)
; #pragma unroll
;         for (int c = 0; c < 8; ++c) { float v = bv[c] + wv[0][c] * x[t][c] + wv[1][c] * x[t + 1][c] + wv[2][c] * x[t + 2][c] + wv[3][c] * x[t + 3][c]; out[t][c] = SILU ? silu_f(v) : v; }
; }
; DI void ssd_pass1(LAS unsigned char* lds, const Args& a, const LayerP& P, int unit, int wv) {
;     ...
;         { float o[4][8]; conv_compute<true>(rawB[g], P.ssd_cw + 256 + g * 128 + cv * 8, 768, P.ssd_cb + 256 + g * 128 + cv * 8, o);
; #pragma unroll
;           for (int k = 0; k < 8; ++k) { u32x2 v; v.x = pk2(o[0][k], o[1][k]); v.y = pk2(o[2][k], o[3][k]); *(LAS u32x2*)(BT + (g * 128 + cv * 8 + k) * PT + t0) = v; } }
	v_pk_fma_f32 v[136:137], v[110:111], v[106:107], v[126:127] op_sel_hi:[0,1,0]
	v_pk_mov_b32 v[106:107], v[106:107], v[108:109] op_sel:[1,0]
	v_pk_fma_f32 v[140:141], v[110:111], v[138:139], v[126:127] op_sel:[1,0,1]
	v_pk_fma_f32 v[106:107], v[114:115], v[106:107], v[136:137] op_sel_hi:[0,1,1]
	v_pk_fma_f32 v[106:107], v[118:119], v[108:109], v[106:107] op_sel_hi:[0,1,1]
	v_pk_fma_f32 v[108:109], v[110:111], v[108:109], v[126:127] op_sel_hi:[0,1,0]
	v_pk_fma_f32 v[108:109], v[114:115], v[130:131], v[108:109] op_sel_hi:[0,1,1]
	v_pk_fma_f32 v[108:109], v[118:119], v[132:133], v[108:109] op_sel_hi:[0,1,1]
	v_pk_fma_f32 v[108:109], v[122:123], v[134:135], v[108:109] op_sel_hi:[0,1,1]
	v_pk_fma_f32 v[106:107], v[122:123], v[130:131], v[106:107] op_sel_hi:[0,1,1]
	v_mul_f32_e32 v130, 0xbfb8aa3b, v108
	v_mul_f32_e32 v131, 0xbfb8aa3b, v109
	v_exp_f32_e32 v130, v130
	v_exp_f32_e32 v131, v131
	v_and_b32_e32 v133, 0xffff0000, v70
	v_mul_f32_e32 v136, 0xbfb8aa3b, v106
	v_add_f32_e32 v130, 1.0, v130
	v_add_f32_e32 v131, 1.0, v131
	v_rcp_f32_e32 v130, v130
	v_rcp_f32_e32 v131, v131
	v_mul_f32_e32 v137, 0xbfb8aa3b, v107
	v_exp_f32_e32 v136, v136
	v_exp_f32_e32 v137, v137
	v_pk_mul_f32 v[108:109], v[108:109], v[130:131]
	v_and_b32_e32 v131, 0xffff0000, v82
	v_and_b32_e32 v130, 0xffff0000, v66
	v_pk_mov_b32 v[138:139], v[138:139], v[130:131] op_sel:[1,0]
	v_mov_b32_e32 v132, v131
	v_pk_fma_f32 v[138:139], v[114:115], v[138:139], v[140:141] op_sel:[1,0,0]
	v_add_f32_e32 v136, 1.0, v136
	v_pk_fma_f32 v[138:139], v[118:119], v[130:131], v[138:139] op_sel:[1,0,0]
	v_add_f32_e32 v137, 1.0, v137
	v_pk_fma_f32 v[138:139], v[122:123], v[132:133], v[138:139] op_sel:[1,0,0]
	v_rcp_f32_e32 v136, v136
	v_mul_f32_e32 v58, 0xbfb8aa3b, v138
	v_exp_f32_e32 v58, v58
	v_rcp_f32_e32 v137, v137
	v_pk_fma_f32 v[110:111], v[110:111], v[130:131], v[126:127] op_sel:[1,0,1]
	v_and_b32_e32 v135, 0xffff0000, v90
	v_add_f32_e32 v58, 1.0, v58
	v_rcp_f32_e32 v140, v58
	v_mul_f32_e32 v58, 0xbfb8aa3b, v139
	v_exp_f32_e32 v58, v58
	v_mov_b32_e32 v134, v133
	v_pk_fma_f32 v[110:111], v[114:115], v[132:133], v[110:111] op_sel:[1,0,0]
	v_pk_mul_f32 v[106:107], v[106:107], v[136:137]
	v_and_b32_e32 v137, 0xffff0000, v86
	v_mov_b32_e32 v136, v135
	v_pk_fma_f32 v[110:111], v[118:119], v[134:135], v[110:111] op_sel:[1,0,0]
	v_add_f32_e32 v58, 1.0, v58
	v_pk_fma_f32 v[110:111], v[122:123], v[136:137], v[110:111] op_sel:[1,0,0]
	v_rcp_f32_e32 v141, v58
	v_mul_f32_e32 v58, 0xbfb8aa3b, v110
	v_exp_f32_e32 v58, v58
	v_lshlrev_b32_e32 v130, 16, v59
	v_lshlrev_b32_e32 v131, 16, v63
	v_pk_fma_f32 v[132:133], v[112:113], v[130:131], v[128:129] op_sel_hi:[0,1,0]
	v_add_f32_e32 v58, 1.0, v58
	v_rcp_f32_e32 v114, v58
	v_mul_f32_e32 v58, 0xbfb8aa3b, v111
	v_exp_f32_e32 v58, v58
	v_lshlrev_b32_e32 v119, 16, v71
	v_lshlrev_b32_e32 v123, 16, v91
	v_mov_b32_e32 v122, v119
	v_add_f32_e32 v58, 1.0, v58
	v_rcp_f32_e32 v115, v58
	v_lshlrev_b32_e32 v127, 16, v87
	v_mov_b32_e32 v126, v123
	v_and_b32_e32 v82, 0xffff0000, v67
	v_pk_mul_f32 v[110:111], v[110:111], v[114:115]
	v_lshlrev_b32_e32 v114, 16, v67
	v_lshlrev_b32_e32 v115, 16, v83
	v_pk_mov_b32 v[130:131], v[130:131], v[114:115] op_sel:[1,0]
	v_mov_b32_e32 v118, v115
	v_pk_fma_f32 v[130:131], v[116:117], v[130:131], v[132:133] op_sel_hi:[0,1,1]
	v_pk_fma_f32 v[130:131], v[120:121], v[114:115], v[130:131] op_sel_hi:[0,1,1]
	v_pk_fma_f32 v[130:131], v[124:125], v[118:119], v[130:131] op_sel_hi:[0,1,1]
	v_mul_f32_e32 v58, 0xbfb8aa3b, v130
	v_exp_f32_e32 v58, v58
	v_pk_fma_f32 v[114:115], v[112:113], v[114:115], v[128:129] op_sel_hi:[0,1,0]
	v_pk_fma_f32 v[114:115], v[116:117], v[118:119], v[114:115] op_sel_hi:[0,1,1]
	v_pk_fma_f32 v[114:115], v[120:121], v[122:123], v[114:115] op_sel_hi:[0,1,1]
	v_add_f32_e32 v58, 1.0, v58
	v_rcp_f32_e32 v132, v58
	v_mul_f32_e32 v58, 0xbfb8aa3b, v131
	v_exp_f32_e32 v58, v58
	v_pk_fma_f32 v[114:115], v[124:125], v[126:127], v[114:115] op_sel_hi:[0,1,1]
	v_and_b32_e32 v83, 0xffff0000, v83
	v_and_b32_e32 v63, 0xffff0000, v63
	v_add_f32_e32 v58, 1.0, v58
	v_rcp_f32_e32 v133, v58
	v_mul_f32_e32 v58, 0xbfb8aa3b, v114
	v_exp_f32_e32 v58, v58
	v_mov_b32_e32 v90, v129
	v_mov_b32_e32 v116, v117
	v_and_b32_e32 v67, 0xffff0000, v71
	v_add_f32_e32 v58, 1.0, v58
	v_rcp_f32_e32 v118, v58
	v_mul_f32_e32 v58, 0xbfb8aa3b, v115
	v_exp_f32_e32 v58, v58
	v_mov_b32_e32 v66, v83
	v_and_b32_e32 v71, 0xffff0000, v91
	v_mov_b32_e32 v70, v67
	v_add_f32_e32 v58, 1.0, v58
	v_rcp_f32_e32 v119, v58
	v_mov_b32_e32 v58, v113
	v_pk_fma_f32 v[112:113], v[58:59], v[62:63], v[90:91] op_sel_hi:[0,1,0]
	v_pk_mov_b32 v[62:63], v[62:63], v[82:83] op_sel:[1,0]
	v_pk_mul_f32 v[114:115], v[114:115], v[118:119]
	v_pk_fma_f32 v[62:63], v[116:117], v[62:63], v[112:113] op_sel_hi:[0,1,1]
	v_mov_b32_e32 v112, v121
	v_pk_fma_f32 v[62:63], v[112:113], v[82:83], v[62:63] op_sel_hi:[0,1,1]
	v_mov_b32_e32 v118, v125
	v_pk_fma_f32 v[62:63], v[118:119], v[66:67], v[62:63] op_sel_hi:[0,1,1]
	v_mul_f32_e32 v59, 0xbfb8aa3b, v62
	v_exp_f32_e32 v59, v59
	v_and_b32_e32 v87, 0xffff0000, v87
	v_mov_b32_e32 v86, v71
	v_pk_mul_f32 v[138:139], v[138:139], v[140:141]
	v_add_f32_e32 v59, 1.0, v59
	v_rcp_f32_e32 v120, v59
	v_mul_f32_e32 v59, 0xbfb8aa3b, v63
	v_exp_f32_e32 v59, v59
	v_pk_mul_f32 v[130:131], v[130:131], v[132:133]
	v_add_f32_e32 v59, 1.0, v59
	v_rcp_f32_e32 v121, v59
	v_pk_fma_f32 v[58:59], v[58:59], v[82:83], v[90:91] op_sel_hi:[0,1,0]
	v_pk_fma_f32 v[58:59], v[116:117], v[66:67], v[58:59] op_sel_hi:[0,1,1]
	v_pk_fma_f32 v[58:59], v[112:113], v[70:71], v[58:59] op_sel_hi:[0,1,1]
	v_pk_fma_f32 v[58:59], v[118:119], v[86:87], v[58:59] op_sel_hi:[0,1,1]
	v_mul_f32_e32 v66, 0xbfb8aa3b, v58
; #define LAS __attribute__((address_space(3)))
; DI unsigned pk2(float lo, float hi) { const f32x2 v = {lo, hi}; const hwbf16x2 b = __builtin_convertvector(v, hwbf16x2); return __builtin_bit_cast(unsigned, b); }
; DI float silu_f(float x) { return x * __builtin_amdgcn_rcpf(1.0f + __expf(-x)); }
; template <bool SILU>
; DI void conv_compute(const u32x4 (&raw)[7], const float* w, int C, const float* bias, float (&out)[4][8]) {
;     float wv[4][8], bv[8], x[7][8];
; #pragma unroll
;     for (int j = 0; j < 4; ++j) { const f32x4 a = *(const f32x4*)(w + (size_t)j * C), b = *(const f32x4*)(w + (size_t)j * C + 4);
;         wv[j][0] = a[0]; wv[j][1] = a[1]; wv[j][2] = a[2]; wv[j][3] = a[3]; wv[j][4] = b[0]; wv[j][5] = b[1]; wv[j][6] = b[2]; wv[j][7] = b[3]; }
;     { const f32x4 a = *(const f32x4*)bias, b = *(const f32x4*)(bias + 4); bv[0] = a[0]; bv[1] = a[1]; bv[2] = a[2]; bv[3] = a[3]; bv[4] = b[0]; bv[5] = b[1]; bv[6] = b[2]; bv[7] = b[3]; }
; #pragma unroll
;     for (int i = 0; i < 7; ++i) unpack8(raw[i], x[i]);
; #pragma unroll
;     for (int t = 0; t < 4; ++t)
; #pragma unroll
;         for (int c = 0; c < 8; ++c) { float v = bv[c] + wv[0][c] * x[t][c] + wv[1][c] * x[t + 1][c] + wv[2][c] * x[t + 2][c] + wv[3][c] * x[t + 3][c]; out[t][c] = SILU ? silu_f(v) : v; }
; }
; DI void ssd_pass1(LAS unsigned char* lds, const Args& a, const LayerP& P, int unit, int wv) {
;     ...
;         { float o[4][8]; conv_compute<true>(rawB[g], P.ssd_cw + 256 + g * 128 + cv * 8, 768, P.ssd_cb + 256 + g * 128 + cv * 8, o);
; #pragma unroll
;           for (int k = 0; k < 8; ++k) { u32x2 v; v.x = pk2(o[0][k], o[1][k]); v.y = pk2(o[2][k], o[3][k]); *(LAS u32x2*)(BT + (g * 128 + cv * 8 + k) * PT + t0) = v; } }
	v_mul_f32_e32 v67, 0xbfb8aa3b, v59
	v_exp_f32_e32 v66, v66
	v_exp_f32_e32 v67, v67
	v_lshlrev_b32_e32 v91, 16, v64
	v_lshlrev_b32_e32 v90, 16, v60
	v_add_f32_e32 v66, 1.0, v66
	v_add_f32_e32 v67, 1.0, v67
	v_rcp_f32_e32 v66, v66
	v_rcp_f32_e32 v67, v67
	v_pk_fma_f32 v[112:113], v[78:79], v[90:91], v[102:103] op_sel_hi:[0,1,0]
	v_lshlrev_b32_e32 v71, 16, v72
	v_lshlrev_b32_e32 v83, 16, v92
	v_pk_mul_f32 v[58:59], v[58:59], v[66:67]
	v_lshlrev_b32_e32 v67, 16, v84
	v_lshlrev_b32_e32 v66, 16, v68
	v_pk_mov_b32 v[90:91], v[90:91], v[66:67] op_sel:[1,0]
	v_mov_b32_e32 v70, v67
	v_pk_fma_f32 v[90:91], v[74:75], v[90:91], v[112:113] op_sel_hi:[0,1,1]
	v_pk_fma_f32 v[90:91], v[94:95], v[66:67], v[90:91] op_sel_hi:[0,1,1]
	v_pk_fma_f32 v[66:67], v[78:79], v[66:67], v[102:103] op_sel_hi:[0,1,0]
	v_mov_b32_e32 v82, v71
	v_pk_fma_f32 v[66:67], v[74:75], v[70:71], v[66:67] op_sel_hi:[0,1,1]
	v_lshlrev_b32_e32 v87, 16, v88
	v_mov_b32_e32 v86, v83
	v_pk_fma_f32 v[66:67], v[94:95], v[82:83], v[66:67] op_sel_hi:[0,1,1]
	v_pk_fma_f32 v[66:67], v[98:99], v[86:87], v[66:67] op_sel_hi:[0,1,1]
	v_pk_fma_f32 v[90:91], v[98:99], v[70:71], v[90:91] op_sel_hi:[0,1,1]
	v_mul_f32_e32 v70, 0xbfb8aa3b, v66
	v_mul_f32_e32 v71, 0xbfb8aa3b, v67
	v_exp_f32_e32 v70, v70
	v_exp_f32_e32 v71, v71
	v_and_b32_e32 v117, 0xffff0000, v64
	v_and_b32_e32 v116, 0xffff0000, v60
	v_add_f32_e32 v70, 1.0, v70
	v_add_f32_e32 v71, 1.0, v71
	v_rcp_f32_e32 v70, v70
	v_rcp_f32_e32 v71, v71
	v_pk_fma_f32 v[118:119], v[78:79], v[116:117], v[102:103] op_sel:[1,0,1]
	v_and_b32_e32 v83, 0xffff0000, v72
	v_mul_f32_e32 v112, 0xbfb8aa3b, v90
	v_pk_mul_f32 v[66:67], v[66:67], v[70:71]
	v_and_b32_e32 v71, 0xffff0000, v84
	v_and_b32_e32 v70, 0xffff0000, v68
	v_pk_mov_b32 v[116:117], v[116:117], v[70:71] op_sel:[1,0]
	v_mov_b32_e32 v82, v71
	v_pk_fma_f32 v[116:117], v[74:75], v[116:117], v[118:119] op_sel:[1,0,0]
	v_mul_f32_e32 v113, 0xbfb8aa3b, v91
	v_pk_fma_f32 v[116:117], v[94:95], v[70:71], v[116:117] op_sel:[1,0,0]
	v_exp_f32_e32 v112, v112
	v_pk_fma_f32 v[116:117], v[98:99], v[82:83], v[116:117] op_sel:[1,0,0]
	v_exp_f32_e32 v113, v113
	v_mul_f32_e32 v60, 0xbfb8aa3b, v116
	v_exp_f32_e32 v60, v60
	v_add_f32_e32 v112, 1.0, v112
	v_add_f32_e32 v113, 1.0, v113
	v_rcp_f32_e32 v112, v112
	v_add_f32_e32 v60, 1.0, v60
	v_rcp_f32_e32 v113, v113
	v_rcp_f32_e32 v118, v60
	v_mul_f32_e32 v60, 0xbfb8aa3b, v117
	v_exp_f32_e32 v60, v60
	v_pk_fma_f32 v[70:71], v[78:79], v[70:71], v[102:103] op_sel:[1,0,1]
	v_and_b32_e32 v87, 0xffff0000, v92
	v_mov_b32_e32 v86, v83
	v_pk_fma_f32 v[70:71], v[74:75], v[82:83], v[70:71] op_sel:[1,0,0]
	v_pk_mul_f32 v[90:91], v[90:91], v[112:113]
	v_and_b32_e32 v113, 0xffff0000, v88
	v_mov_b32_e32 v112, v87
	v_pk_fma_f32 v[70:71], v[94:95], v[86:87], v[70:71] op_sel:[1,0,0]
	v_add_f32_e32 v60, 1.0, v60
	v_pk_fma_f32 v[70:71], v[98:99], v[112:113], v[70:71] op_sel:[1,0,0]
	v_rcp_f32_e32 v119, v60
	v_mul_f32_e32 v60, 0xbfb8aa3b, v70
	v_exp_f32_e32 v60, v60
	v_lshlrev_b32_e32 v94, 16, v61
	v_lshlrev_b32_e32 v95, 16, v65
	v_pk_fma_f32 v[98:99], v[80:81], v[94:95], v[104:105] op_sel_hi:[0,1,0]
	v_add_f32_e32 v60, 1.0, v60
	v_rcp_f32_e32 v74, v60
	v_mul_f32_e32 v60, 0xbfb8aa3b, v71
	v_exp_f32_e32 v60, v60
	v_lshlrev_b32_e32 v79, 16, v73
	v_lshlrev_b32_e32 v83, 16, v93
	v_mov_b32_e32 v82, v79
	v_add_f32_e32 v60, 1.0, v60
	v_rcp_f32_e32 v75, v60
	v_lshlrev_b32_e32 v87, 16, v89
	v_mov_b32_e32 v86, v83
	v_and_b32_e32 v65, 0xffff0000, v65
	v_pk_mul_f32 v[70:71], v[70:71], v[74:75]
	v_lshlrev_b32_e32 v74, 16, v69
	v_lshlrev_b32_e32 v75, 16, v85
	v_pk_mov_b32 v[94:95], v[94:95], v[74:75] op_sel:[1,0]
	v_mov_b32_e32 v78, v75
	v_pk_fma_f32 v[94:95], v[76:77], v[94:95], v[98:99] op_sel_hi:[0,1,1]
	v_pk_fma_f32 v[94:95], v[96:97], v[74:75], v[94:95] op_sel_hi:[0,1,1]
	v_pk_fma_f32 v[94:95], v[100:101], v[78:79], v[94:95] op_sel_hi:[0,1,1]
	v_mul_f32_e32 v60, 0xbfb8aa3b, v94
	v_exp_f32_e32 v60, v60
	v_pk_fma_f32 v[74:75], v[80:81], v[74:75], v[104:105] op_sel_hi:[0,1,0]
	v_pk_fma_f32 v[74:75], v[76:77], v[78:79], v[74:75] op_sel_hi:[0,1,1]
	v_pk_fma_f32 v[74:75], v[96:97], v[82:83], v[74:75] op_sel_hi:[0,1,1]
	v_add_f32_e32 v60, 1.0, v60
	v_rcp_f32_e32 v98, v60
	v_mul_f32_e32 v60, 0xbfb8aa3b, v95
	v_exp_f32_e32 v60, v60
	v_pk_fma_f32 v[74:75], v[100:101], v[86:87], v[74:75] op_sel_hi:[0,1,1]
	v_and_b32_e32 v64, 0xffff0000, v61
	v_mov_b32_e32 v76, v105
	v_add_f32_e32 v60, 1.0, v60
	v_rcp_f32_e32 v99, v60
	v_mul_f32_e32 v60, 0xbfb8aa3b, v74
	v_exp_f32_e32 v60, v60
	v_mov_b32_e32 v84, v77
	v_mov_b32_e32 v86, v101
	v_and_b32_e32 v83, 0xffff0000, v89
	v_add_f32_e32 v60, 1.0, v60
	v_rcp_f32_e32 v78, v60
	v_mul_f32_e32 v60, 0xbfb8aa3b, v75
	v_exp_f32_e32 v60, v60
	v_pk_mul_f32 v[62:63], v[62:63], v[120:121]
	v_pk_mul_f32 v[98:99], v[94:95], v[98:99]
	v_pk_mul_f32 v[116:117], v[116:117], v[118:119]
	v_add_f32_e32 v60, 1.0, v60
	v_rcp_f32_e32 v79, v60
	v_mov_b32_e32 v60, v81
	v_pk_fma_f32 v[80:81], v[60:61], v[64:65], v[76:77] op_sel_hi:[0,1,0]
	v_cvt_pk_bf16_f32 v62, v62, v63
	v_pk_mul_f32 v[74:75], v[74:75], v[78:79]
	v_and_b32_e32 v79, 0xffff0000, v85
	v_and_b32_e32 v78, 0xffff0000, v69
	v_pk_mov_b32 v[64:65], v[64:65], v[78:79] op_sel:[1,0]
	v_and_b32_e32 v69, 0xffff0000, v73
	v_pk_fma_f32 v[64:65], v[84:85], v[64:65], v[80:81] op_sel_hi:[0,1,1]
	v_mov_b32_e32 v80, v97
	v_mov_b32_e32 v68, v79
	v_pk_fma_f32 v[64:65], v[80:81], v[78:79], v[64:65] op_sel_hi:[0,1,1]
	v_pk_fma_f32 v[64:65], v[86:87], v[68:69], v[64:65] op_sel_hi:[0,1,1]
	v_mul_f32_e32 v61, 0xbfb8aa3b, v64
	v_exp_f32_e32 v61, v61
	v_and_b32_e32 v73, 0xffff0000, v93
	v_mov_b32_e32 v72, v69
	v_mov_b32_e32 v82, v73
	v_add_f32_e32 v61, 1.0, v61
; #define LAS __attribute__((address_space(3)))
; DI unsigned pk2(float lo, float hi) { const f32x2 v = {lo, hi}; const hwbf16x2 b = __builtin_convertvector(v, hwbf16x2); return __builtin_bit_cast(unsigned, b); }
; DI void ssd_pass1(LAS unsigned char* lds, const Args& a, const LayerP& P, int unit, int wv) {
;     ...
;         { float o[4][8]; conv_compute<true>(rawX[g], P.ssd_cw + g * 128 + cv * 8, 768, P.ssd_cb + g * 128 + cv * 8, o);
;           const int h = 2 * g + (cv >> 3); const float ae = acs[h * 128 + 127]; float w[4];
; #pragma unroll
;           for (int t = 0; t < 4; ++t) w[t] = __expf(ae - acs[h * 128 + t0 + t]) * dtl[h * 128 + t0 + t];
; #pragma unroll
;           for (int k = 0; k < 8; ++k) { u32x2 v; v.x = pk2(o[0][k] * w[0], o[1][k] * w[1]); v.y = pk2(o[2][k] * w[2], o[3][k] * w[3]); *(LAS u32x2*)(XT + (h * 64 + (cv & 7) * 8 + k) * PT + t0) = v; } }
;         { float o[4][8]; conv_compute<true>(rawB[g], P.ssd_cw + 256 + g * 128 + cv * 8, 768, P.ssd_cb + 256 + g * 128 + cv * 8, o);
; #pragma unroll
;           for (int k = 0; k < 8; ++k) { u32x2 v; v.x = pk2(o[0][k], o[1][k]); v.y = pk2(o[2][k], o[3][k]); *(LAS u32x2*)(BT + (g * 128 + cv * 8 + k) * PT + t0) = v; } }
	v_rcp_f32_e32 v88, v61
	v_mul_f32_e32 v61, 0xbfb8aa3b, v65
	v_exp_f32_e32 v61, v61
	v_cvt_pk_bf16_f32 v63, v58, v59
	v_cvt_pk_bf16_f32 v58, v90, v91
	v_cvt_pk_bf16_f32 v59, v66, v67
	v_add_f32_e32 v61, 1.0, v61
	v_rcp_f32_e32 v89, v61
	v_pk_fma_f32 v[60:61], v[60:61], v[78:79], v[76:77] op_sel_hi:[0,1,0]
	v_pk_fma_f32 v[60:61], v[84:85], v[68:69], v[60:61] op_sel_hi:[0,1,1]
	v_pk_fma_f32 v[60:61], v[80:81], v[72:73], v[60:61] op_sel_hi:[0,1,1]
	v_pk_fma_f32 v[60:61], v[86:87], v[82:83], v[60:61] op_sel_hi:[0,1,1]
	v_mul_f32_e32 v68, 0xbfb8aa3b, v60
	v_mul_f32_e32 v69, 0xbfb8aa3b, v61
	v_exp_f32_e32 v68, v68
	v_exp_f32_e32 v69, v69
	v_mul_u32_u24_e32 v72, 0x880, v166
	v_add3_u32 v94, 0, v172, v72
	v_add_f32_e32 v68, 1.0, v68
	v_add_f32_e32 v69, 1.0, v69
	v_rcp_f32_e32 v68, v68
	v_rcp_f32_e32 v69, v69
	v_cvt_pk_bf16_f32 v72, v138, v139
	v_cvt_pk_bf16_f32 v73, v110, v111
	v_pk_mul_f32 v[64:65], v[64:65], v[88:89]
	v_pk_mul_f32 v[60:61], v[60:61], v[68:69]
	v_cvt_pk_bf16_f32 v68, v106, v107
	v_cvt_pk_bf16_f32 v69, v108, v109
	ds_write2_b64 v94, v[68:69], v[72:73] offset1:34
	global_store_dwordx2 v220, v[68:69], s[92:93]
	global_store_dwordx2 v220, v[72:73], s[92:93] offset:8
	v_cvt_pk_bf16_f32 v68, v130, v131
	v_cvt_pk_bf16_f32 v69, v114, v115
	ds_write2_b64 v94, v[68:69], v[62:63] offset0:68 offset1:102
	global_store_dwordx2 v220, v[68:69], s[92:93] offset:16
	global_store_dwordx2 v220, v[62:63], s[92:93] offset:24
	v_cvt_pk_bf16_f32 v62, v116, v117
	v_cvt_pk_bf16_f32 v63, v70, v71
	ds_write2_b64 v94, v[58:59], v[62:63] offset0:136 offset1:170
	global_store_dwordx2 v220, v[58:59], s[92:93] offset:32
	global_store_dwordx2 v220, v[62:63], s[92:93] offset:40
	v_cvt_pk_bf16_f32 v58, v98, v99
	v_cvt_pk_bf16_f32 v59, v74, v75
	v_cvt_pk_bf16_f32 v62, v64, v65
	v_cvt_pk_bf16_f32 v63, v60, v61
	v_lshl_add_u64 v[66:67], v[156:157], 0, s[12:13]
	s_mov_b64 s[12:13], 0x2600
	ds_write2_b64 v94, v[58:59], v[62:63] offset0:204 offset1:238
	global_store_dwordx2 v220, v[58:59], s[92:93] offset:48
	global_store_dwordx2 v220, v[62:63], s[92:93] offset:56
	v_lshl_add_u64 v[82:83], v[156:157], 0, s[12:13]
	global_load_dwordx4 v[62:65], v0, s[42:43] offset:528
	global_load_dwordx4 v[74:77], v0, s[42:43] offset:512
	global_load_dwordx4 v[58:61], v0, s[42:43] offset:3600
	global_load_dwordx4 v[70:73], v0, s[42:43] offset:3584
	global_load_dwordx4 v[78:81], v[158:159], off offset:2560
	s_nop 0
	global_load_dwordx4 v[66:69], v[66:67], off offset:16
	s_nop 0
	global_load_dwordx4 v[96:99], v[154:155], off offset:1536
	s_nop 0
	global_load_dwordx4 v[82:85], v[82:83], off offset:16
	s_nop 0
	global_load_dwordx4 v[86:89], v0, s[46:47] offset:528
	global_load_dwordx4 v[100:103], v0, s[46:47] offset:512
	v_or_b32_e32 v95, 2, v170
	v_lshl_add_u32 v90, v95, 9, s3
	ds_read_b32 v104, v90 offset:508
	v_add_u32_e32 v90, v90, v171
	ds_read_b128 v[90:93], v90
	v_lshlrev_b32_e32 v111, 16, v42
	v_lshlrev_b32_e32 v110, 16, v38
	v_lshlrev_b32_e32 v113, 16, v50
	v_mov_b32_e32 v112, v111
	s_waitcnt lgkmcnt(0)
	v_sub_f32_e32 v90, v104, v90
	v_mul_f32_e32 v90, 0x3fb8aa3b, v90
	v_exp_f32_e32 v108, v90
	v_sub_f32_e32 v90, v104, v91
	v_mul_f32_e32 v90, 0x3fb8aa3b, v90
	v_lshl_add_u32 v105, v95, 7, v167
	v_exp_f32_e32 v109, v90
	v_sub_f32_e32 v90, v104, v92
	v_sub_f32_e32 v91, v104, v93
	v_lshlrev_b32_e32 v93, 16, v46
	v_mov_b32_e32 v92, v113
	v_lshl_add_u32 v116, v105, 2, s2
	v_lshlrev_b32_e32 v105, 16, v54
	v_mov_b32_e32 v104, v93
	v_mul_f32_e32 v90, 0x3fb8aa3b, v90
	v_mul_f32_e32 v91, 0x3fb8aa3b, v91
	v_exp_f32_e32 v90, v90
	v_exp_f32_e32 v91, v91
	v_lshl_or_b32 v95, v95, 6, v169
	v_mad_u32_u24 v95, v95, s56, v168
	s_mov_b64 s[2:3], 0x600
	s_waitcnt vmcnt(0)
	v_pk_fma_f32 v[106:107], v[74:75], v[110:111], v[100:101] op_sel_hi:[0,1,0]
	v_pk_fma_f32 v[106:107], v[70:71], v[112:113], v[106:107] op_sel_hi:[0,1,1]
	v_pk_fma_f32 v[92:93], v[78:79], v[92:93], v[106:107] op_sel_hi:[0,1,1]
	v_pk_fma_f32 v[92:93], v[96:97], v[104:105], v[92:93] op_sel_hi:[0,1,1]
	v_mul_f32_e32 v104, 0xbfb8aa3b, v92
	v_mul_f32_e32 v105, 0xbfb8aa3b, v93
	v_exp_f32_e32 v104, v104
	v_exp_f32_e32 v105, v105
	v_add_f32_e32 v104, 1.0, v104
	v_add_f32_e32 v105, 1.0, v105
	v_rcp_f32_e32 v104, v104
	v_rcp_f32_e32 v105, v105
	s_nop 0
	v_pk_mul_f32 v[114:115], v[92:93], v[104:105]
	ds_read_b128 v[104:107], v116
	s_waitcnt lgkmcnt(0)
; #define LAS __attribute__((address_space(3)))
; DI unsigned pk2(float lo, float hi) { const f32x2 v = {lo, hi}; const hwbf16x2 b = __builtin_convertvector(v, hwbf16x2); return __builtin_bit_cast(unsigned, b); }
; DI float silu_f(float x) { return x * __builtin_amdgcn_rcpf(1.0f + __expf(-x)); }
; template <bool SILU>
; DI void conv_compute(const u32x4 (&raw)[7], const float* w, int C, const float* bias, float (&out)[4][8]) {
;     float wv[4][8], bv[8], x[7][8];
; #pragma unroll
;     for (int j = 0; j < 4; ++j) { const f32x4 a = *(const f32x4*)(w + (size_t)j * C), b = *(const f32x4*)(w + (size_t)j * C + 4);
;         wv[j][0] = a[0]; wv[j][1] = a[1]; wv[j][2] = a[2]; wv[j][3] = a[3]; wv[j][4] = b[0]; wv[j][5] = b[1]; wv[j][6] = b[2]; wv[j][7] = b[3]; }
;     { const f32x4 a = *(const f32x4*)bias, b = *(const f32x4*)(bias + 4); bv[0] = a[0]; bv[1] = a[1]; bv[2] = a[2]; bv[3] = a[3]; bv[4] = b[0]; bv[5] = b[1]; bv[6] = b[2]; bv[7] = b[3]; }
; #pragma unroll
;     for (int i = 0; i < 7; ++i) unpack8(raw[i], x[i]);
; #pragma unroll
;     for (int t = 0; t < 4; ++t)
; #pragma unroll
;         for (int c = 0; c < 8; ++c) { float v = bv[c] + wv[0][c] * x[t][c] + wv[1][c] * x[t + 1][c] + wv[2][c] * x[t + 2][c] + wv[3][c] * x[t + 3][c]; out[t][c] = SILU ? silu_f(v) : v; }
; }
; DI void ssd_pass1(LAS unsigned char* lds, const Args& a, const LayerP& P, int unit, int wv) {
;     ...
;         { float o[4][8]; conv_compute<true>(rawX[g], P.ssd_cw + g * 128 + cv * 8, 768, P.ssd_cb + g * 128 + cv * 8, o);
;           const int h = 2 * g + (cv >> 3); const float ae = acs[h * 128 + 127]; float w[4];
; #pragma unroll
;           for (int t = 0; t < 4; ++t) w[t] = __expf(ae - acs[h * 128 + t0 + t]) * dtl[h * 128 + t0 + t];
; #pragma unroll
;           for (int k = 0; k < 8; ++k) { u32x2 v; v.x = pk2(o[0][k] * w[0], o[1][k] * w[1]); v.y = pk2(o[2][k] * w[2], o[3][k] * w[3]); *(LAS u32x2*)(XT + (h * 64 + (cv & 7) * 8 + k) * PT + t0) = v; } }
	v_pk_mul_f32 v[90:91], v[106:107], v[90:91]
	v_lshlrev_b32_e32 v107, 16, v34
	v_lshlrev_b32_e32 v106, 16, v30
	v_pk_fma_f32 v[116:117], v[74:75], v[106:107], v[100:101] op_sel_hi:[0,1,0]
	v_pk_mul_f32 v[92:93], v[104:105], v[108:109]
	v_pk_mov_b32 v[104:105], v[106:107], v[110:111] op_sel:[1,0]
	v_and_b32_e32 v109, 0xffff0000, v50
	v_pk_fma_f32 v[104:105], v[70:71], v[104:105], v[116:117] op_sel_hi:[0,1,1]
	v_pk_fma_f32 v[104:105], v[78:79], v[110:111], v[104:105] op_sel_hi:[0,1,1]
	v_pk_fma_f32 v[104:105], v[96:97], v[112:113], v[104:105] op_sel_hi:[0,1,1]
	v_mul_f32_e32 v106, 0xbfb8aa3b, v104
	v_mul_f32_e32 v107, 0xbfb8aa3b, v105
	v_exp_f32_e32 v106, v106
	v_exp_f32_e32 v107, v107
	v_and_b32_e32 v111, 0xffff0000, v46
	v_mov_b32_e32 v110, v109
	v_add_f32_e32 v106, 1.0, v106
	v_add_f32_e32 v107, 1.0, v107
	v_rcp_f32_e32 v106, v106
	v_rcp_f32_e32 v107, v107
	v_and_b32_e32 v113, 0xffff0000, v54
	v_mov_b32_e32 v112, v111
	v_pk_mul_f32 v[104:105], v[104:105], v[106:107]
	s_nop 0
	v_pk_mul_f32 v[104:105], v[92:93], v[104:105]
	v_pk_mul_f32 v[106:107], v[114:115], v[90:91]
	v_cvt_pk_bf16_f32 v104, v104, v105
	v_cvt_pk_bf16_f32 v105, v106, v107
	v_and_b32_e32 v107, 0xffff0000, v42
	v_and_b32_e32 v106, 0xffff0000, v38
	v_mov_b32_e32 v108, v107
	v_pk_fma_f32 v[114:115], v[74:75], v[106:107], v[100:101] op_sel:[1,0,1]
	v_and_b32_e32 v42, 0xffff0000, v39
	v_pk_fma_f32 v[114:115], v[70:71], v[108:109], v[114:115] op_sel:[1,0,0]
	s_nop 0
	v_pk_fma_f32 v[110:111], v[78:79], v[110:111], v[114:115] op_sel:[1,0,0]
	s_nop 0
	v_pk_fma_f32 v[110:111], v[96:97], v[112:113], v[110:111] op_sel:[1,0,0]
	s_nop 0
	v_mul_f32_e32 v38, 0xbfb8aa3b, v110
	v_exp_f32_e32 v38, v38
	s_nop 0
	v_add_f32_e32 v38, 1.0, v38
	v_rcp_f32_e32 v112, v38
	v_mul_f32_e32 v38, 0xbfb8aa3b, v111
	v_exp_f32_e32 v38, v38
	s_nop 0
	v_add_f32_e32 v38, 1.0, v38
	v_rcp_f32_e32 v113, v38
	s_nop 0
	v_pk_mul_f32 v[110:111], v[110:111], v[112:113]
	v_and_b32_e32 v113, 0xffff0000, v34
	v_and_b32_e32 v112, 0xffff0000, v30
	v_pk_fma_f32 v[74:75], v[74:75], v[112:113], v[100:101] op_sel:[1,0,1]
	v_pk_mov_b32 v[100:101], v[112:113], v[106:107] op_sel:[1,0]
	v_mov_b32_e32 v34, v103
	v_pk_fma_f32 v[70:71], v[70:71], v[100:101], v[74:75] op_sel:[1,0,0]
	s_nop 0
	v_pk_fma_f32 v[70:71], v[78:79], v[106:107], v[70:71] op_sel:[1,0,0]
	v_lshlrev_b32_e32 v79, 16, v47
	v_pk_fma_f32 v[70:71], v[96:97], v[108:109], v[70:71] op_sel:[1,0,0]
	v_lshlrev_b32_e32 v97, 16, v55
	v_mul_f32_e32 v30, 0xbfb8aa3b, v70
	v_exp_f32_e32 v30, v30
	v_mov_b32_e32 v96, v79
	v_and_b32_e32 v47, 0xffff0000, v47
	v_mov_b32_e32 v50, v47
	v_add_f32_e32 v30, 1.0, v30
	v_rcp_f32_e32 v74, v30
	v_mul_f32_e32 v30, 0xbfb8aa3b, v71
	v_exp_f32_e32 v30, v30
	s_nop 0
	v_add_f32_e32 v30, 1.0, v30
	v_rcp_f32_e32 v75, v30
	s_nop 0
	v_pk_mul_f32 v[70:71], v[70:71], v[74:75]
	s_nop 0
	v_pk_mul_f32 v[70:71], v[92:93], v[70:71]
	v_pk_mul_f32 v[74:75], v[110:111], v[90:91]
	v_cvt_pk_bf16_f32 v70, v70, v71
	v_cvt_pk_bf16_f32 v71, v74, v75
	ds_write2_b64 v95, v[104:105], v[70:71] offset1:34
	v_lshlrev_b32_e32 v70, 16, v39
	v_lshlrev_b32_e32 v71, 16, v43
	v_lshlrev_b32_e32 v75, 16, v51
	v_mov_b32_e32 v74, v71
	v_pk_fma_f32 v[100:101], v[76:77], v[70:71], v[102:103] op_sel_hi:[0,1,0]
	v_mov_b32_e32 v78, v75
	v_pk_fma_f32 v[100:101], v[72:73], v[74:75], v[100:101] op_sel_hi:[0,1,1]
	v_pk_fma_f32 v[78:79], v[80:81], v[78:79], v[100:101] op_sel_hi:[0,1,1]
	v_pk_fma_f32 v[78:79], v[98:99], v[96:97], v[78:79] op_sel_hi:[0,1,1]
	v_mul_f32_e32 v30, 0xbfb8aa3b, v78
	v_exp_f32_e32 v30, v30
	v_and_b32_e32 v43, 0xffff0000, v43
	v_and_b32_e32 v39, 0xffff0000, v51
	v_mov_b32_e32 v38, v43
	v_add_f32_e32 v30, 1.0, v30
	v_rcp_f32_e32 v96, v30
	v_mul_f32_e32 v30, 0xbfb8aa3b, v79
	v_exp_f32_e32 v30, v30
	v_and_b32_e32 v51, 0xffff0000, v55
	v_mov_b32_e32 v46, v39
	v_add_f32_e32 v30, 1.0, v30
	v_rcp_f32_e32 v97, v30
	s_nop 0
	v_pk_mul_f32 v[78:79], v[78:79], v[96:97]
	v_lshlrev_b32_e32 v96, 16, v31
	v_lshlrev_b32_e32 v97, 16, v35
	v_pk_fma_f32 v[100:101], v[76:77], v[96:97], v[102:103] op_sel_hi:[0,1,0]
	v_pk_mov_b32 v[96:97], v[96:97], v[70:71] op_sel:[1,0]
	s_nop 0
	v_pk_fma_f32 v[96:97], v[72:73], v[96:97], v[100:101] op_sel_hi:[0,1,1]
	v_pk_fma_f32 v[70:71], v[80:81], v[70:71], v[96:97] op_sel_hi:[0,1,1]
	v_pk_fma_f32 v[70:71], v[98:99], v[74:75], v[70:71] op_sel_hi:[0,1,1]
	v_mul_f32_e32 v30, 0xbfb8aa3b, v70
	v_exp_f32_e32 v30, v30
	v_mov_b32_e32 v72, v73
	v_add_f32_e32 v30, 1.0, v30
	v_rcp_f32_e32 v74, v30
	v_mul_f32_e32 v30, 0xbfb8aa3b, v71
	v_exp_f32_e32 v30, v30
	s_nop 0
	v_add_f32_e32 v30, 1.0, v30
	v_rcp_f32_e32 v75, v30
	v_mov_b32_e32 v30, v77
	v_pk_fma_f32 v[54:55], v[30:31], v[42:43], v[34:35] op_sel_hi:[0,1,0]
	v_pk_fma_f32 v[54:55], v[72:73], v[38:39], v[54:55] op_sel_hi:[0,1,1]
	v_pk_mul_f32 v[70:71], v[70:71], v[74:75]
	v_pk_mul_f32 v[74:75], v[78:79], v[90:91]
	v_pk_mul_f32 v[70:71], v[92:93], v[70:71]
	v_lshlrev_b32_e32 v77, 16, v26
	v_cvt_pk_bf16_f32 v70, v70, v71
	v_cvt_pk_bf16_f32 v71, v74, v75
	v_mov_b32_e32 v74, v81
	v_pk_fma_f32 v[46:47], v[74:75], v[46:47], v[54:55] op_sel_hi:[0,1,1]
	v_mov_b32_e32 v54, v99
	v_pk_fma_f32 v[46:47], v[54:55], v[50:51], v[46:47] op_sel_hi:[0,1,1]
	v_mul_f32_e32 v50, 0xbfb8aa3b, v46
	v_mul_f32_e32 v51, 0xbfb8aa3b, v47
	v_exp_f32_e32 v50, v50
	v_exp_f32_e32 v51, v51
	v_lshlrev_b32_e32 v79, 16, v22
	v_mov_b32_e32 v78, v77
	v_add_f32_e32 v50, 1.0, v50
	v_add_f32_e32 v51, 1.0, v51
	v_rcp_f32_e32 v50, v50
	v_rcp_f32_e32 v51, v51
	s_nop 0
	v_pk_mul_f32 v[46:47], v[46:47], v[50:51]
	v_and_b32_e32 v51, 0xffff0000, v35
	v_and_b32_e32 v50, 0xffff0000, v31
	v_pk_fma_f32 v[30:31], v[30:31], v[50:51], v[34:35] op_sel_hi:[0,1,0]
; #define LAS __attribute__((address_space(3)))
; DI unsigned pk2(float lo, float hi) { const f32x2 v = {lo, hi}; const hwbf16x2 b = __builtin_convertvector(v, hwbf16x2); return __builtin_bit_cast(unsigned, b); }
; DI float silu_f(float x) { return x * __builtin_amdgcn_rcpf(1.0f + __expf(-x)); }
; template <bool SILU>
; DI void conv_compute(const u32x4 (&raw)[7], const float* w, int C, const float* bias, float (&out)[4][8]) {
;     float wv[4][8], bv[8], x[7][8];
; #pragma unroll
;     for (int j = 0; j < 4; ++j) { const f32x4 a = *(const f32x4*)(w + (size_t)j * C), b = *(const f32x4*)(w + (size_t)j * C + 4);
;         wv[j][0] = a[0]; wv[j][1] = a[1]; wv[j][2] = a[2]; wv[j][3] = a[3]; wv[j][4] = b[0]; wv[j][5] = b[1]; wv[j][6] = b[2]; wv[j][7] = b[3]; }
;     { const f32x4 a = *(const f32x4*)bias, b = *(const f32x4*)(bias + 4); bv[0] = a[0]; bv[1] = a[1]; bv[2] = a[2]; bv[3] = a[3]; bv[4] = b[0]; bv[5] = b[1]; bv[6] = b[2]; bv[7] = b[3]; }
; #pragma unroll
;     for (int i = 0; i < 7; ++i) unpack8(raw[i], x[i]);
; #pragma unroll
;     for (int t = 0; t < 4; ++t)
; #pragma unroll
;         for (int c = 0; c < 8; ++c) { float v = bv[c] + wv[0][c] * x[t][c] + wv[1][c] * x[t + 1][c] + wv[2][c] * x[t + 2][c] + wv[3][c] * x[t + 3][c]; out[t][c] = SILU ? silu_f(v) : v; }
; }
; DI void ssd_pass1(LAS unsigned char* lds, const Args& a, const LayerP& P, int unit, int wv) {
;     ...
;         { float o[4][8]; conv_compute<true>(rawX[g], P.ssd_cw + g * 128 + cv * 8, 768, P.ssd_cb + g * 128 + cv * 8, o);
;           const int h = 2 * g + (cv >> 3); const float ae = acs[h * 128 + 127]; float w[4];
; #pragma unroll
;           for (int t = 0; t < 4; ++t) w[t] = __expf(ae - acs[h * 128 + t0 + t]) * dtl[h * 128 + t0 + t];
; #pragma unroll
;           for (int k = 0; k < 8; ++k) { u32x2 v; v.x = pk2(o[0][k] * w[0], o[1][k] * w[1]); v.y = pk2(o[2][k] * w[2], o[3][k] * w[3]); *(LAS u32x2*)(XT + (h * 64 + (cv & 7) * 8 + k) * PT + t0) = v; } }
	v_pk_mov_b32 v[34:35], v[50:51], v[42:43] op_sel:[1,0]
	s_nop 0
	v_pk_fma_f32 v[30:31], v[72:73], v[34:35], v[30:31] op_sel_hi:[0,1,1]
	v_pk_fma_f32 v[30:31], v[74:75], v[42:43], v[30:31] op_sel_hi:[0,1,1]
	v_pk_fma_f32 v[30:31], v[54:55], v[38:39], v[30:31] op_sel_hi:[0,1,1]
	v_mul_f32_e32 v34, 0xbfb8aa3b, v30
	v_mul_f32_e32 v35, 0xbfb8aa3b, v31
	v_exp_f32_e32 v34, v34
	v_exp_f32_e32 v35, v35
	v_lshlrev_b32_e32 v39, 16, v48
	v_lshlrev_b32_e32 v43, 16, v56
	v_add_f32_e32 v34, 1.0, v34
	v_add_f32_e32 v35, 1.0, v35
	v_rcp_f32_e32 v34, v34
	v_rcp_f32_e32 v35, v35
	v_mov_b32_e32 v42, v39
	v_lshlrev_b32_e32 v73, 16, v18
	v_lshlrev_b32_e32 v72, 16, v10
	v_pk_mul_f32 v[30:31], v[30:31], v[34:35]
	v_pk_mul_f32 v[34:35], v[46:47], v[90:91]
	v_pk_mul_f32 v[30:31], v[92:93], v[30:31]
	v_lshlrev_b32_e32 v75, 16, v14
	v_cvt_pk_bf16_f32 v30, v30, v31
	v_cvt_pk_bf16_f32 v31, v34, v35
	ds_write2_b64 v95, v[70:71], v[30:31] offset0:68 offset1:102
	v_lshlrev_b32_e32 v31, 16, v44
	v_lshlrev_b32_e32 v30, 16, v40
	v_lshlrev_b32_e32 v35, 16, v52
	v_mov_b32_e32 v34, v31
	v_pk_fma_f32 v[46:47], v[62:63], v[30:31], v[86:87] op_sel_hi:[0,1,0]
	v_mov_b32_e32 v38, v35
	v_pk_fma_f32 v[46:47], v[58:59], v[34:35], v[46:47] op_sel_hi:[0,1,1]
	v_pk_fma_f32 v[38:39], v[66:67], v[38:39], v[46:47] op_sel_hi:[0,1,1]
	v_pk_fma_f32 v[38:39], v[82:83], v[42:43], v[38:39] op_sel_hi:[0,1,1]
	v_mul_f32_e32 v42, 0xbfb8aa3b, v38
	v_mul_f32_e32 v43, 0xbfb8aa3b, v39
	v_exp_f32_e32 v42, v42
	v_exp_f32_e32 v43, v43
	v_lshlrev_b32_e32 v71, 16, v6
	v_lshlrev_b32_e32 v70, 16, v2
	v_add_f32_e32 v42, 1.0, v42
	v_add_f32_e32 v43, 1.0, v43
	v_rcp_f32_e32 v42, v42
	v_rcp_f32_e32 v43, v43
	v_mov_b32_e32 v74, v73
	v_mov_b32_e32 v76, v75
	v_pk_mul_f32 v[38:39], v[38:39], v[42:43]
	v_lshlrev_b32_e32 v43, 16, v36
	v_lshlrev_b32_e32 v42, 16, v32
	v_pk_fma_f32 v[46:47], v[62:63], v[42:43], v[86:87] op_sel_hi:[0,1,0]
	v_pk_mov_b32 v[42:43], v[42:43], v[30:31] op_sel:[1,0]
	s_nop 0
	v_pk_fma_f32 v[42:43], v[58:59], v[42:43], v[46:47] op_sel_hi:[0,1,1]
	v_pk_fma_f32 v[30:31], v[66:67], v[30:31], v[42:43] op_sel_hi:[0,1,1]
	v_pk_fma_f32 v[30:31], v[82:83], v[34:35], v[30:31] op_sel_hi:[0,1,1]
	v_mul_f32_e32 v34, 0xbfb8aa3b, v30
	v_mul_f32_e32 v35, 0xbfb8aa3b, v31
	v_exp_f32_e32 v34, v34
	v_exp_f32_e32 v35, v35
	v_and_b32_e32 v43, 0xffff0000, v48
	v_and_b32_e32 v47, 0xffff0000, v56
	v_add_f32_e32 v34, 1.0, v34
	v_add_f32_e32 v35, 1.0, v35
	v_rcp_f32_e32 v34, v34
	v_rcp_f32_e32 v35, v35
	v_mov_b32_e32 v46, v43
	v_mov_b32_e32 v48, v69
	v_pk_mul_f32 v[30:31], v[30:31], v[34:35]
	s_nop 0
	v_pk_mul_f32 v[30:31], v[92:93], v[30:31]
	v_pk_mul_f32 v[34:35], v[38:39], v[90:91]
	v_cvt_pk_bf16_f32 v30, v30, v31
	v_cvt_pk_bf16_f32 v31, v34, v35
	v_and_b32_e32 v35, 0xffff0000, v44
	v_and_b32_e32 v34, 0xffff0000, v40
	v_and_b32_e32 v39, 0xffff0000, v52
	v_mov_b32_e32 v38, v35
	v_pk_fma_f32 v[50:51], v[62:63], v[34:35], v[86:87] op_sel:[1,0,1]
	v_mov_b32_e32 v42, v39
	v_pk_fma_f32 v[50:51], v[58:59], v[38:39], v[50:51] op_sel:[1,0,0]
	s_nop 0
	v_pk_fma_f32 v[42:43], v[66:67], v[42:43], v[50:51] op_sel:[1,0,0]
	s_nop 0
	v_pk_fma_f32 v[42:43], v[82:83], v[46:47], v[42:43] op_sel:[1,0,0]
	s_nop 0
	v_mul_f32_e32 v40, 0xbfb8aa3b, v42
	v_exp_f32_e32 v40, v40
	s_nop 0
	v_add_f32_e32 v40, 1.0, v40
	v_rcp_f32_e32 v46, v40
	v_mul_f32_e32 v40, 0xbfb8aa3b, v43
	v_exp_f32_e32 v40, v40
	s_nop 0
	v_add_f32_e32 v40, 1.0, v40
	v_rcp_f32_e32 v47, v40
	s_nop 0
	v_pk_mul_f32 v[42:43], v[42:43], v[46:47]
	v_and_b32_e32 v47, 0xffff0000, v36
	v_and_b32_e32 v46, 0xffff0000, v32
	v_pk_fma_f32 v[50:51], v[62:63], v[46:47], v[86:87] op_sel:[1,0,1]
	v_pk_mov_b32 v[46:47], v[46:47], v[34:35] op_sel:[1,0]
	v_mov_b32_e32 v36, v89
	v_pk_fma_f32 v[46:47], v[58:59], v[46:47], v[50:51] op_sel:[1,0,0]
	s_nop 0
	v_pk_fma_f32 v[34:35], v[66:67], v[34:35], v[46:47] op_sel:[1,0,0]
	s_nop 0
	v_pk_fma_f32 v[34:35], v[82:83], v[38:39], v[34:35] op_sel:[1,0,0]
	v_and_b32_e32 v83, 0xffff0000, v22
	v_mul_f32_e32 v32, 0xbfb8aa3b, v34
	v_exp_f32_e32 v32, v32
	s_nop 0
	v_add_f32_e32 v32, 1.0, v32
	v_rcp_f32_e32 v38, v32
	v_mul_f32_e32 v32, 0xbfb8aa3b, v35
	v_exp_f32_e32 v32, v32
	s_nop 0
	v_add_f32_e32 v32, 1.0, v32
	v_rcp_f32_e32 v39, v32
	s_nop 0
	v_pk_mul_f32 v[34:35], v[34:35], v[38:39]
	s_nop 0
	v_pk_mul_f32 v[34:35], v[92:93], v[34:35]
	v_pk_mul_f32 v[38:39], v[42:43], v[90:91]
	v_cvt_pk_bf16_f32 v34, v34, v35
	v_cvt_pk_bf16_f32 v35, v38, v39
	ds_write2_b64 v95, v[30:31], v[34:35] offset0:136 offset1:170
	v_lshlrev_b32_e32 v30, 16, v41
	v_lshlrev_b32_e32 v31, 16, v45
	v_lshlrev_b32_e32 v35, 16, v53
	v_mov_b32_e32 v34, v31
	v_pk_fma_f32 v[46:47], v[64:65], v[30:31], v[88:89] op_sel_hi:[0,1,0]
	v_lshlrev_b32_e32 v39, 16, v49
	v_mov_b32_e32 v38, v35
	v_pk_fma_f32 v[46:47], v[60:61], v[34:35], v[46:47] op_sel_hi:[0,1,1]
	v_lshlrev_b32_e32 v43, 16, v57
	v_mov_b32_e32 v42, v39
	v_pk_fma_f32 v[38:39], v[68:69], v[38:39], v[46:47] op_sel_hi:[0,1,1]
	v_pk_fma_f32 v[38:39], v[84:85], v[42:43], v[38:39] op_sel_hi:[0,1,1]
	v_mul_f32_e32 v32, 0xbfb8aa3b, v38
	v_exp_f32_e32 v32, v32
	s_nop 0
	v_add_f32_e32 v32, 1.0, v32
	v_rcp_f32_e32 v42, v32
	v_mul_f32_e32 v32, 0xbfb8aa3b, v39
	v_exp_f32_e32 v32, v32
	s_nop 0
	v_add_f32_e32 v32, 1.0, v32
	v_rcp_f32_e32 v43, v32
	s_nop 0
	v_pk_mul_f32 v[38:39], v[38:39], v[42:43]
	v_lshlrev_b32_e32 v42, 16, v33
	v_lshlrev_b32_e32 v43, 16, v37
	v_pk_fma_f32 v[46:47], v[64:65], v[42:43], v[88:89] op_sel_hi:[0,1,0]
	v_pk_mov_b32 v[42:43], v[42:43], v[30:31] op_sel:[1,0]
	s_nop 0
	v_pk_fma_f32 v[42:43], v[60:61], v[42:43], v[46:47] op_sel_hi:[0,1,1]
	v_pk_fma_f32 v[30:31], v[68:69], v[30:31], v[42:43] op_sel_hi:[0,1,1]
; #define LAS __attribute__((address_space(3)))
; DI unsigned pk2(float lo, float hi) { const f32x2 v = {lo, hi}; const hwbf16x2 b = __builtin_convertvector(v, hwbf16x2); return __builtin_bit_cast(unsigned, b); }
; DI float silu_f(float x) { return x * __builtin_amdgcn_rcpf(1.0f + __expf(-x)); }
; template <bool SILU>
; DI void conv_compute(const u32x4 (&raw)[7], const float* w, int C, const float* bias, float (&out)[4][8]) {
;     float wv[4][8], bv[8], x[7][8];
; #pragma unroll
;     for (int j = 0; j < 4; ++j) { const f32x4 a = *(const f32x4*)(w + (size_t)j * C), b = *(const f32x4*)(w + (size_t)j * C + 4);
;         wv[j][0] = a[0]; wv[j][1] = a[1]; wv[j][2] = a[2]; wv[j][3] = a[3]; wv[j][4] = b[0]; wv[j][5] = b[1]; wv[j][6] = b[2]; wv[j][7] = b[3]; }
;     { const f32x4 a = *(const f32x4*)bias, b = *(const f32x4*)(bias + 4); bv[0] = a[0]; bv[1] = a[1]; bv[2] = a[2]; bv[3] = a[3]; bv[4] = b[0]; bv[5] = b[1]; bv[6] = b[2]; bv[7] = b[3]; }
; #pragma unroll
;     for (int i = 0; i < 7; ++i) unpack8(raw[i], x[i]);
; #pragma unroll
;     for (int t = 0; t < 4; ++t)
; #pragma unroll
;         for (int c = 0; c < 8; ++c) { float v = bv[c] + wv[0][c] * x[t][c] + wv[1][c] * x[t + 1][c] + wv[2][c] * x[t + 2][c] + wv[3][c] * x[t + 3][c]; out[t][c] = SILU ? silu_f(v) : v; }
; }
; DI void ssd_pass1(LAS unsigned char* lds, const Args& a, const LayerP& P, int unit, int wv) {
;     ...
;           for (int k = 0; k < 8; ++k) { u32x2 v; v.x = pk2(o[0][k] * w[0], o[1][k] * w[1]); v.y = pk2(o[2][k] * w[2], o[3][k] * w[3]); *(LAS u32x2*)(XT + (h * 64 + (cv & 7) * 8 + k) * PT + t0) = v; } }
;         { float o[4][8]; conv_compute<true>(rawB[g], P.ssd_cw + 256 + g * 128 + cv * 8, 768, P.ssd_cb + 256 + g * 128 + cv * 8, o);
	v_pk_fma_f32 v[30:31], v[84:85], v[34:35], v[30:31] op_sel_hi:[0,1,1]
	v_mul_f32_e32 v32, 0xbfb8aa3b, v30
	v_exp_f32_e32 v32, v32
	v_mov_b32_e32 v46, v61
	v_and_b32_e32 v43, 0xffff0000, v57
	v_add_f32_e32 v32, 1.0, v32
	v_rcp_f32_e32 v34, v32
	v_mul_f32_e32 v32, 0xbfb8aa3b, v31
	v_exp_f32_e32 v32, v32
	s_nop 0
	v_add_f32_e32 v32, 1.0, v32
	v_rcp_f32_e32 v35, v32
	v_mov_b32_e32 v32, v65
	v_pk_mul_f32 v[30:31], v[30:31], v[34:35]
	s_nop 0
	v_pk_mul_f32 v[30:31], v[92:93], v[30:31]
	v_pk_mul_f32 v[34:35], v[38:39], v[90:91]
	v_cvt_pk_bf16_f32 v30, v30, v31
	v_cvt_pk_bf16_f32 v31, v34, v35
	v_and_b32_e32 v35, 0xffff0000, v45
	v_and_b32_e32 v34, 0xffff0000, v41
	v_and_b32_e32 v39, 0xffff0000, v53
	v_mov_b32_e32 v38, v35
	v_pk_fma_f32 v[44:45], v[32:33], v[34:35], v[36:37] op_sel_hi:[0,1,0]
	v_and_b32_e32 v41, 0xffff0000, v49
	v_mov_b32_e32 v40, v39
	v_pk_fma_f32 v[44:45], v[46:47], v[38:39], v[44:45] op_sel_hi:[0,1,1]
	v_mov_b32_e32 v42, v41
	v_pk_fma_f32 v[40:41], v[48:49], v[40:41], v[44:45] op_sel_hi:[0,1,1]
	v_mov_b32_e32 v44, v85
	v_pk_fma_f32 v[40:41], v[44:45], v[42:43], v[40:41] op_sel_hi:[0,1,1]
	v_mul_f32_e32 v42, 0xbfb8aa3b, v40
	v_mul_f32_e32 v43, 0xbfb8aa3b, v41
	v_exp_f32_e32 v42, v42
	v_exp_f32_e32 v43, v43
	v_add_f32_e32 v42, 1.0, v42
	v_add_f32_e32 v43, 1.0, v43
	v_rcp_f32_e32 v42, v42
	v_rcp_f32_e32 v43, v43
	s_nop 0
	v_pk_mul_f32 v[40:41], v[40:41], v[42:43]
	v_and_b32_e32 v43, 0xffff0000, v37
	v_and_b32_e32 v42, 0xffff0000, v33
	v_pk_fma_f32 v[32:33], v[32:33], v[42:43], v[36:37] op_sel_hi:[0,1,0]
	v_pk_mov_b32 v[36:37], v[42:43], v[34:35] op_sel:[1,0]
	s_nop 0
	v_pk_fma_f32 v[32:33], v[46:47], v[36:37], v[32:33] op_sel_hi:[0,1,1]
	v_pk_fma_f32 v[32:33], v[48:49], v[34:35], v[32:33] op_sel_hi:[0,1,1]
	v_pk_fma_f32 v[32:33], v[44:45], v[38:39], v[32:33] op_sel_hi:[0,1,1]
	v_mul_f32_e32 v34, 0xbfb8aa3b, v32
	v_mul_f32_e32 v35, 0xbfb8aa3b, v33
	v_exp_f32_e32 v34, v34
	v_exp_f32_e32 v35, v35
	v_lshl_add_u64 v[38:39], v[156:157], 0, s[2:3]
	s_mov_b64 s[2:3], 0x1e00
	v_add_f32_e32 v34, 1.0, v34
	v_add_f32_e32 v35, 1.0, v35
	v_rcp_f32_e32 v34, v34
	v_rcp_f32_e32 v35, v35
	v_lshl_add_u64 v[46:47], v[156:157], 0, s[2:3]
	s_mov_b64 s[2:3], 0x2a00
	v_lshl_add_u64 v[50:51], v[156:157], 0, s[2:3]
	v_pk_mul_f32 v[32:33], v[32:33], v[34:35]
	v_pk_mul_f32 v[34:35], v[40:41], v[90:91]
	v_pk_mul_f32 v[32:33], v[92:93], v[32:33]
	v_readlane_b32 s2, v254, 37
	v_cvt_pk_bf16_f32 v32, v32, v33
	v_cvt_pk_bf16_f32 v33, v34, v35
	ds_write2_b64 v95, v[30:31], v[32:33] offset0:204 offset1:238
	global_load_dwordx4 v[34:37], v0, s[42:43] offset:1552
	global_load_dwordx4 v[42:45], v0, s[42:43] offset:1536
	global_load_dwordx4 v[30:33], v[38:39], off offset:3088
	s_nop 0
	global_load_dwordx4 v[38:41], v[38:39], off offset:3072
	s_nop 0
	global_load_dwordx4 v[54:57], v[158:159], off offset:3584
	s_nop 0
	global_load_dwordx4 v[46:49], v[46:47], off offset:16
	s_nop 0
	global_load_dwordx4 v[58:61], v[154:155], off offset:2560
	s_nop 0
	global_load_dwordx4 v[50:53], v[50:51], off offset:16
	s_nop 0
	global_load_dwordx4 v[62:65], v0, s[46:47] offset:1552
	global_load_dwordx4 v[66:69], v0, s[46:47] offset:1536
	s_waitcnt vmcnt(0)
	v_pk_fma_f32 v[80:81], v[42:43], v[70:71], v[66:67] op_sel_hi:[0,1,0]
	v_pk_mov_b32 v[70:71], v[70:71], v[72:73] op_sel:[1,0]
	s_nop 0
	v_pk_fma_f32 v[70:71], v[38:39], v[70:71], v[80:81] op_sel_hi:[0,1,1]
	v_pk_fma_f32 v[70:71], v[54:55], v[72:73], v[70:71] op_sel_hi:[0,1,1]
	v_pk_fma_f32 v[70:71], v[58:59], v[74:75], v[70:71] op_sel_hi:[0,1,1]
	v_mul_f32_e32 v0, 0xbfb8aa3b, v70
	v_exp_f32_e32 v0, v0
	v_pk_fma_f32 v[72:73], v[42:43], v[72:73], v[66:67] op_sel_hi:[0,1,0]
	v_pk_fma_f32 v[72:73], v[38:39], v[74:75], v[72:73] op_sel_hi:[0,1,1]
	v_pk_fma_f32 v[72:73], v[54:55], v[76:77], v[72:73] op_sel_hi:[0,1,1]
	v_add_f32_e32 v0, 1.0, v0
	v_rcp_f32_e32 v80, v0
	v_mul_f32_e32 v0, 0xbfb8aa3b, v71
	v_exp_f32_e32 v0, v0
	v_pk_fma_f32 v[72:73], v[58:59], v[78:79], v[72:73] op_sel_hi:[0,1,1]
	v_and_b32_e32 v77, 0xffff0000, v18
	v_and_b32_e32 v76, 0xffff0000, v10
	v_add_f32_e32 v0, 1.0, v0
	v_rcp_f32_e32 v81, v0
	v_mul_f32_e32 v0, 0xbfb8aa3b, v72
	v_exp_f32_e32 v0, v0
	v_and_b32_e32 v79, 0xffff0000, v14
	v_mov_b32_e32 v78, v77
	v_pk_mul_f32 v[70:71], v[70:71], v[80:81]
	v_add_f32_e32 v0, 1.0, v0
	v_rcp_f32_e32 v74, v0
	v_mul_f32_e32 v0, 0xbfb8aa3b, v73
	v_exp_f32_e32 v0, v0
	v_and_b32_e32 v81, 0xffff0000, v26
	v_mov_b32_e32 v80, v79
	v_mov_b32_e32 v82, v81
	v_add_f32_e32 v0, 1.0, v0
	v_rcp_f32_e32 v75, v0
	v_and_b32_e32 v18, 0xffff0000, v11
	v_mov_b32_e32 v26, v69
	v_pk_mul_f32 v[72:73], v[72:73], v[74:75]
	v_and_b32_e32 v75, 0xffff0000, v6
	v_and_b32_e32 v74, 0xffff0000, v2
	v_pk_fma_f32 v[84:85], v[42:43], v[74:75], v[66:67] op_sel:[1,0,1]
	v_pk_mov_b32 v[74:75], v[74:75], v[76:77] op_sel:[1,0]
	v_pk_fma_f32 v[42:43], v[42:43], v[76:77], v[66:67] op_sel:[1,0,1]
	v_pk_fma_f32 v[74:75], v[38:39], v[74:75], v[84:85] op_sel:[1,0,0]
	v_pk_fma_f32 v[38:39], v[38:39], v[78:79], v[42:43] op_sel:[1,0,0]
	v_pk_fma_f32 v[74:75], v[54:55], v[76:77], v[74:75] op_sel:[1,0,0]
	v_pk_fma_f32 v[38:39], v[54:55], v[80:81], v[38:39] op_sel:[1,0,0]
	v_pk_fma_f32 v[74:75], v[58:59], v[78:79], v[74:75] op_sel:[1,0,0]
	v_pk_fma_f32 v[38:39], v[58:59], v[82:83], v[38:39] op_sel:[1,0,0]
	v_mul_f32_e32 v0, 0xbfb8aa3b, v74
	v_exp_f32_e32 v0, v0
	v_lshlrev_b32_e32 v54, 16, v11
	v_lshlrev_b32_e32 v55, 16, v19
	v_lshlrev_b32_e32 v59, 16, v15
	v_add_f32_e32 v0, 1.0, v0
	v_rcp_f32_e32 v84, v0
	v_mul_f32_e32 v0, 0xbfb8aa3b, v75
	v_exp_f32_e32 v0, v0
	v_mov_b32_e32 v58, v55
	v_lshlrev_b32_e32 v67, 16, v27
	v_mov_b32_e32 v66, v59
	v_add_f32_e32 v0, 1.0, v0
	v_rcp_f32_e32 v85, v0
; #define LAS __attribute__((address_space(3)))
; DI unsigned pk2(float lo, float hi) { const f32x2 v = {lo, hi}; const hwbf16x2 b = __builtin_convertvector(v, hwbf16x2); return __builtin_bit_cast(unsigned, b); }
; DI float silu_f(float x) { return x * __builtin_amdgcn_rcpf(1.0f + __expf(-x)); }
; template <bool SILU>
; DI void conv_compute(const u32x4 (&raw)[7], const float* w, int C, const float* bias, float (&out)[4][8]) {
;     float wv[4][8], bv[8], x[7][8];
; #pragma unroll
;     for (int j = 0; j < 4; ++j) { const f32x4 a = *(const f32x4*)(w + (size_t)j * C), b = *(const f32x4*)(w + (size_t)j * C + 4);
;         wv[j][0] = a[0]; wv[j][1] = a[1]; wv[j][2] = a[2]; wv[j][3] = a[3]; wv[j][4] = b[0]; wv[j][5] = b[1]; wv[j][6] = b[2]; wv[j][7] = b[3]; }
;     { const f32x4 a = *(const f32x4*)bias, b = *(const f32x4*)(bias + 4); bv[0] = a[0]; bv[1] = a[1]; bv[2] = a[2]; bv[3] = a[3]; bv[4] = b[0]; bv[5] = b[1]; bv[6] = b[2]; bv[7] = b[3]; }
; #pragma unroll
;     for (int i = 0; i < 7; ++i) unpack8(raw[i], x[i]);
; #pragma unroll
;     for (int t = 0; t < 4; ++t)
; #pragma unroll
;         for (int c = 0; c < 8; ++c) { float v = bv[c] + wv[0][c] * x[t][c] + wv[1][c] * x[t + 1][c] + wv[2][c] * x[t + 2][c] + wv[3][c] * x[t + 3][c]; out[t][c] = SILU ? silu_f(v) : v; }
; }
; DI void ssd_pass1(LAS unsigned char* lds, const Args& a, const LayerP& P, int unit, int wv) {
;     ...
;         { float o[4][8]; conv_compute<true>(rawB[g], P.ssd_cw + 256 + g * 128 + cv * 8, 768, P.ssd_cb + 256 + g * 128 + cv * 8, o);
; #pragma unroll
;           for (int k = 0; k < 8; ++k) { u32x2 v; v.x = pk2(o[0][k], o[1][k]); v.y = pk2(o[2][k], o[3][k]); *(LAS u32x2*)(BT + (g * 128 + cv * 8 + k) * PT + t0) = v; } }
	v_mul_f32_e32 v0, 0xbfb8aa3b, v38
	v_exp_f32_e32 v0, v0
	v_lshlrev_b32_e32 v77, 16, v23
	v_mov_b32_e32 v76, v67
	v_and_b32_e32 v19, 0xffff0000, v19
	v_add_f32_e32 v0, 1.0, v0
	v_rcp_f32_e32 v42, v0
	v_mul_f32_e32 v0, 0xbfb8aa3b, v39
	v_exp_f32_e32 v0, v0
	v_and_b32_e32 v6, 0xffff0000, v3
	v_and_b32_e32 v11, 0xffff0000, v15
	v_mov_b32_e32 v10, v19
	v_add_f32_e32 v0, 1.0, v0
	v_rcp_f32_e32 v43, v0
	v_and_b32_e32 v15, 0xffff0000, v27
	v_mov_b32_e32 v14, v11
	v_and_b32_e32 v23, 0xffff0000, v23
	v_pk_mul_f32 v[38:39], v[38:39], v[42:43]
	v_lshlrev_b32_e32 v42, 16, v3
	v_lshlrev_b32_e32 v43, 16, v7
	v_pk_fma_f32 v[78:79], v[44:45], v[42:43], v[68:69] op_sel_hi:[0,1,0]
	v_pk_mov_b32 v[42:43], v[42:43], v[54:55] op_sel:[1,0]
	v_and_b32_e32 v7, 0xffff0000, v7
	v_pk_fma_f32 v[42:43], v[40:41], v[42:43], v[78:79] op_sel_hi:[0,1,1]
	v_pk_fma_f32 v[42:43], v[56:57], v[54:55], v[42:43] op_sel_hi:[0,1,1]
	v_pk_fma_f32 v[42:43], v[60:61], v[58:59], v[42:43] op_sel_hi:[0,1,1]
	v_mul_f32_e32 v0, 0xbfb8aa3b, v42
	v_exp_f32_e32 v0, v0
	v_pk_fma_f32 v[54:55], v[44:45], v[54:55], v[68:69] op_sel_hi:[0,1,0]
	v_pk_fma_f32 v[54:55], v[40:41], v[58:59], v[54:55] op_sel_hi:[0,1,1]
	v_pk_fma_f32 v[54:55], v[56:57], v[66:67], v[54:55] op_sel_hi:[0,1,1]
	v_add_f32_e32 v0, 1.0, v0
	v_rcp_f32_e32 v78, v0
	v_mul_f32_e32 v0, 0xbfb8aa3b, v43
	v_exp_f32_e32 v0, v0
	v_pk_fma_f32 v[54:55], v[60:61], v[76:77], v[54:55] op_sel_hi:[0,1,1]
	v_mov_b32_e32 v40, v41
	v_mov_b32_e32 v44, v61
	v_add_f32_e32 v0, 1.0, v0
	v_rcp_f32_e32 v79, v0
	v_mul_f32_e32 v0, 0xbfb8aa3b, v54
	v_exp_f32_e32 v0, v0
	v_mov_b32_e32 v22, v15
	v_pk_mul_f32 v[74:75], v[74:75], v[84:85]
	v_pk_mul_f32 v[42:43], v[42:43], v[78:79]
	v_add_f32_e32 v0, 1.0, v0
	v_rcp_f32_e32 v58, v0
	v_mul_f32_e32 v0, 0xbfb8aa3b, v55
	v_exp_f32_e32 v0, v0
	s_nop 0
	v_add_f32_e32 v0, 1.0, v0
	v_rcp_f32_e32 v59, v0
	v_mov_b32_e32 v0, v45
	v_pk_fma_f32 v[2:3], v[0:1], v[6:7], v[26:27] op_sel_hi:[0,1,0]
	v_pk_mov_b32 v[6:7], v[6:7], v[18:19] op_sel:[1,0]
	v_pk_mul_f32 v[54:55], v[54:55], v[58:59]
	v_pk_fma_f32 v[2:3], v[40:41], v[6:7], v[2:3] op_sel_hi:[0,1,1]
	v_mov_b32_e32 v6, v57
	v_pk_fma_f32 v[2:3], v[6:7], v[18:19], v[2:3] op_sel_hi:[0,1,1]
	v_pk_fma_f32 v[2:3], v[44:45], v[10:11], v[2:3] op_sel_hi:[0,1,1]
	v_mul_f32_e32 v7, 0xbfb8aa3b, v2
	v_exp_f32_e32 v7, v7
	v_pk_fma_f32 v[18:19], v[0:1], v[18:19], v[26:27] op_sel_hi:[0,1,0]
	v_pk_fma_f32 v[10:11], v[40:41], v[10:11], v[18:19] op_sel_hi:[0,1,1]
	v_lshlrev_b32_e32 v19, 16, v16
	v_add_f32_e32 v7, 1.0, v7
	v_rcp_f32_e32 v56, v7
	v_mul_f32_e32 v7, 0xbfb8aa3b, v3
	v_exp_f32_e32 v7, v7
	v_lshlrev_b32_e32 v27, 16, v24
	v_add_f32_e32 v7, 1.0, v7
	v_rcp_f32_e32 v57, v7
	v_pk_fma_f32 v[6:7], v[6:7], v[14:15], v[10:11] op_sel_hi:[0,1,1]
	v_pk_fma_f32 v[6:7], v[44:45], v[22:23], v[6:7] op_sel_hi:[0,1,1]
	v_mul_f32_e32 v0, 0xbfb8aa3b, v6
	v_exp_f32_e32 v0, v0
	v_lshlrev_b32_e32 v15, 16, v20
	v_lshlrev_b32_e32 v14, 16, v12
	v_mov_b32_e32 v18, v15
	v_add_f32_e32 v0, 1.0, v0
	v_rcp_f32_e32 v10, v0
	v_mul_f32_e32 v0, 0xbfb8aa3b, v7
	v_exp_f32_e32 v0, v0
	v_lshlrev_b32_e32 v23, 16, v28
	v_mov_b32_e32 v22, v19
	v_mov_b32_e32 v26, v23
	v_add_f32_e32 v0, 1.0, v0
	v_rcp_f32_e32 v11, v0
	v_pk_mul_f32 v[2:3], v[2:3], v[56:57]
	v_and_b32_e32 v45, 0xffff0000, v24
	v_cvt_pk_bf16_f32 v2, v2, v3
	v_pk_mul_f32 v[6:7], v[6:7], v[10:11]
	v_lshlrev_b32_e32 v11, 16, v8
	v_lshlrev_b32_e32 v10, 16, v4
	v_pk_fma_f32 v[40:41], v[34:35], v[10:11], v[62:63] op_sel_hi:[0,1,0]
	v_pk_mov_b32 v[10:11], v[10:11], v[14:15] op_sel:[1,0]
	v_cvt_pk_bf16_f32 v3, v6, v7
	v_pk_fma_f32 v[10:11], v[30:31], v[10:11], v[40:41] op_sel_hi:[0,1,1]
	v_pk_fma_f32 v[10:11], v[46:47], v[14:15], v[10:11] op_sel_hi:[0,1,1]
	v_pk_fma_f32 v[10:11], v[50:51], v[18:19], v[10:11] op_sel_hi:[0,1,1]
	v_mul_f32_e32 v0, 0xbfb8aa3b, v10
	v_exp_f32_e32 v0, v0
	v_pk_fma_f32 v[14:15], v[34:35], v[14:15], v[62:63] op_sel_hi:[0,1,0]
	v_pk_fma_f32 v[14:15], v[30:31], v[18:19], v[14:15] op_sel_hi:[0,1,1]
	v_pk_fma_f32 v[14:15], v[46:47], v[22:23], v[14:15] op_sel_hi:[0,1,1]
	v_add_f32_e32 v0, 1.0, v0
	v_rcp_f32_e32 v40, v0
	v_mul_f32_e32 v0, 0xbfb8aa3b, v11
	v_exp_f32_e32 v0, v0
	v_pk_fma_f32 v[14:15], v[50:51], v[26:27], v[14:15] op_sel_hi:[0,1,1]
	v_and_b32_e32 v23, 0xffff0000, v20
	v_and_b32_e32 v22, 0xffff0000, v12
	v_add_f32_e32 v0, 1.0, v0
	v_rcp_f32_e32 v41, v0
	v_mul_f32_e32 v0, 0xbfb8aa3b, v14
	v_exp_f32_e32 v0, v0
	v_and_b32_e32 v27, 0xffff0000, v16
	v_mov_b32_e32 v26, v23
	v_pk_mul_f32 v[10:11], v[10:11], v[40:41]
	v_add_f32_e32 v0, 1.0, v0
	v_rcp_f32_e32 v18, v0
	v_mul_f32_e32 v0, 0xbfb8aa3b, v15
	v_exp_f32_e32 v0, v0
	v_and_b32_e32 v41, 0xffff0000, v28
	v_mov_b32_e32 v40, v27
	v_mov_b32_e32 v44, v41
	v_add_f32_e32 v0, 1.0, v0
	v_rcp_f32_e32 v19, v0
	v_and_b32_e32 v20, 0xffff0000, v13
	v_pk_mul_f32 v[14:15], v[14:15], v[18:19]
	v_and_b32_e32 v19, 0xffff0000, v8
	v_and_b32_e32 v18, 0xffff0000, v4
	v_pk_fma_f32 v[56:57], v[34:35], v[18:19], v[62:63] op_sel:[1,0,1]
	v_pk_mov_b32 v[18:19], v[18:19], v[22:23] op_sel:[1,0]
	v_and_b32_e32 v8, 0xffff0000, v5
	v_pk_fma_f32 v[18:19], v[30:31], v[18:19], v[56:57] op_sel:[1,0,0]
	v_mov_b32_e32 v4, v65
	v_pk_fma_f32 v[18:19], v[46:47], v[22:23], v[18:19] op_sel:[1,0,0]
	v_pk_fma_f32 v[22:23], v[34:35], v[22:23], v[62:63] op_sel:[1,0,1]
	v_pk_fma_f32 v[18:19], v[50:51], v[26:27], v[18:19] op_sel:[1,0,0]
	v_pk_fma_f32 v[22:23], v[30:31], v[26:27], v[22:23] op_sel:[1,0,0]
	v_mul_f32_e32 v0, 0xbfb8aa3b, v18
	v_exp_f32_e32 v0, v0
	v_pk_fma_f32 v[22:23], v[46:47], v[40:41], v[22:23] op_sel:[1,0,0]
	v_lshlrev_b32_e32 v31, 16, v17
	v_pk_fma_f32 v[22:23], v[50:51], v[44:45], v[22:23] op_sel:[1,0,0]
; #define LAS __attribute__((address_space(3)))
; DI unsigned pk2(float lo, float hi) { const f32x2 v = {lo, hi}; const hwbf16x2 b = __builtin_convertvector(v, hwbf16x2); return __builtin_bit_cast(unsigned, b); }
; DI void ssd_pass1(LAS unsigned char* lds, const Args& a, const LayerP& P, int unit, int wv) {
;     ...
;         { float o[4][8]; conv_compute<true>(rawB[g], P.ssd_cw + 256 + g * 128 + cv * 8, 768, P.ssd_cb + 256 + g * 128 + cv * 8, o);
; #pragma unroll
;           for (int k = 0; k < 8; ++k) { u32x2 v; v.x = pk2(o[0][k], o[1][k]); v.y = pk2(o[2][k], o[3][k]); *(LAS u32x2*)(BT + (g * 128 + cv * 8 + k) * PT + t0) = v; } }
;     }
;     __syncthreads();
;     const int h = wave >> 1, nb = (wave & 1) * 64, r = lane & 15, q = lane >> 4;
;     f32x4 acc[4][4]; zero_acc(acc);
	v_add_f32_e32 v0, 1.0, v0
	v_rcp_f32_e32 v56, v0
	v_mul_f32_e32 v0, 0xbfb8aa3b, v19
	v_exp_f32_e32 v0, v0
	v_lshlrev_b32_e32 v44, 16, v5
	v_lshlrev_b32_e32 v45, 16, v9
	v_pk_fma_f32 v[46:47], v[36:37], v[44:45], v[64:65] op_sel_hi:[0,1,0]
	v_add_f32_e32 v0, 1.0, v0
	v_rcp_f32_e32 v57, v0
	v_mul_f32_e32 v0, 0xbfb8aa3b, v22
	v_exp_f32_e32 v0, v0
	v_lshlrev_b32_e32 v35, 16, v29
	v_mov_b32_e32 v34, v31
	v_lshlrev_b32_e32 v41, 16, v25
	v_add_f32_e32 v0, 1.0, v0
	v_rcp_f32_e32 v26, v0
	v_mul_f32_e32 v0, 0xbfb8aa3b, v23
	v_exp_f32_e32 v0, v0
	v_mov_b32_e32 v40, v35
	v_and_b32_e32 v9, 0xffff0000, v9
	v_and_b32_e32 v25, 0xffff0000, v25
	v_add_f32_e32 v0, 1.0, v0
	v_rcp_f32_e32 v27, v0
	v_pk_mul_f32 v[18:19], v[18:19], v[56:57]
	v_pk_mul_f32 v[22:23], v[22:23], v[26:27]
	v_lshlrev_b32_e32 v26, 16, v13
	v_lshlrev_b32_e32 v27, 16, v21
	v_pk_mov_b32 v[44:45], v[44:45], v[26:27] op_sel:[1,0]
	v_mov_b32_e32 v30, v27
	v_pk_fma_f32 v[44:45], v[32:33], v[44:45], v[46:47] op_sel_hi:[0,1,1]
	v_pk_fma_f32 v[44:45], v[48:49], v[26:27], v[44:45] op_sel_hi:[0,1,1]
	v_pk_fma_f32 v[44:45], v[52:53], v[30:31], v[44:45] op_sel_hi:[0,1,1]
	v_mul_f32_e32 v0, 0xbfb8aa3b, v44
	v_exp_f32_e32 v0, v0
	v_pk_fma_f32 v[26:27], v[36:37], v[26:27], v[64:65] op_sel_hi:[0,1,0]
	v_pk_fma_f32 v[26:27], v[32:33], v[30:31], v[26:27] op_sel_hi:[0,1,1]
	v_pk_fma_f32 v[26:27], v[48:49], v[34:35], v[26:27] op_sel_hi:[0,1,1]
	v_add_f32_e32 v0, 1.0, v0
	v_rcp_f32_e32 v46, v0
	v_mul_f32_e32 v0, 0xbfb8aa3b, v45
	v_exp_f32_e32 v0, v0
	v_pk_fma_f32 v[26:27], v[52:53], v[40:41], v[26:27] op_sel_hi:[0,1,1]
	v_and_b32_e32 v21, 0xffff0000, v21
	v_and_b32_e32 v13, 0xffff0000, v17
	v_add_f32_e32 v0, 1.0, v0
	v_rcp_f32_e32 v47, v0
	v_mul_f32_e32 v0, 0xbfb8aa3b, v26
	v_exp_f32_e32 v0, v0
	v_and_b32_e32 v17, 0xffff0000, v29
	v_mov_b32_e32 v12, v21
	v_mov_b32_e32 v32, v53
	v_add_f32_e32 v0, 1.0, v0
	v_rcp_f32_e32 v30, v0
	v_mul_f32_e32 v0, 0xbfb8aa3b, v27
	v_exp_f32_e32 v0, v0
	v_mov_b32_e32 v16, v13
	v_mov_b32_e32 v24, v17
	v_pk_mul_f32 v[44:45], v[44:45], v[46:47]
	v_add_f32_e32 v0, 1.0, v0
	v_rcp_f32_e32 v31, v0
	v_mov_b32_e32 v0, v37
	v_pk_fma_f32 v[28:29], v[0:1], v[8:9], v[4:5] op_sel_hi:[0,1,0]
	v_pk_mov_b32 v[8:9], v[8:9], v[20:21] op_sel:[1,0]
	v_pk_mul_f32 v[26:27], v[26:27], v[30:31]
	v_mov_b32_e32 v30, v33
	v_pk_fma_f32 v[8:9], v[30:31], v[8:9], v[28:29] op_sel_hi:[0,1,1]
	v_mov_b32_e32 v28, v49
	v_pk_fma_f32 v[8:9], v[28:29], v[20:21], v[8:9] op_sel_hi:[0,1,1]
	v_pk_fma_f32 v[8:9], v[32:33], v[12:13], v[8:9] op_sel_hi:[0,1,1]
	v_mul_f32_e32 v5, 0xbfb8aa3b, v8
	v_exp_f32_e32 v5, v5
	v_cvt_pk_bf16_f32 v6, v18, v19
	v_cvt_pk_bf16_f32 v7, v22, v23
	v_add_f32_e32 v5, 1.0, v5
	v_rcp_f32_e32 v34, v5
	v_mul_f32_e32 v5, 0xbfb8aa3b, v9
	v_exp_f32_e32 v5, v5
	s_nop 0
	v_add_f32_e32 v5, 1.0, v5
	v_rcp_f32_e32 v35, v5
	v_pk_fma_f32 v[4:5], v[0:1], v[20:21], v[4:5] op_sel_hi:[0,1,0]
	v_pk_fma_f32 v[4:5], v[30:31], v[12:13], v[4:5] op_sel_hi:[0,1,1]
	v_pk_fma_f32 v[4:5], v[28:29], v[16:17], v[4:5] op_sel_hi:[0,1,1]
	v_pk_fma_f32 v[4:5], v[32:33], v[24:25], v[4:5] op_sel_hi:[0,1,1]
	v_mul_f32_e32 v0, 0xbfb8aa3b, v4
	v_exp_f32_e32 v0, v0
	v_cvt_pk_bf16_f32 v16, v74, v75
	v_cvt_pk_bf16_f32 v17, v38, v39
	v_pk_mul_f32 v[8:9], v[8:9], v[34:35]
	v_add_f32_e32 v0, 1.0, v0
	v_rcp_f32_e32 v12, v0
	v_mul_f32_e32 v0, 0xbfb8aa3b, v5
	v_exp_f32_e32 v0, v0
	s_nop 0
	v_add_f32_e32 v0, 1.0, v0
	v_rcp_f32_e32 v13, v0
	v_add_u32_e32 v0, 0x8800, v94
	v_pk_mul_f32 v[4:5], v[4:5], v[12:13]
	v_cvt_pk_bf16_f32 v12, v70, v71
	v_cvt_pk_bf16_f32 v13, v72, v73
	ds_write2_b64 v0, v[12:13], v[16:17] offset1:34
	global_store_dwordx2 v221, v[12:13], s[92:93]
	global_store_dwordx2 v221, v[16:17], s[92:93] offset:8
	v_cvt_pk_bf16_f32 v12, v42, v43
	v_cvt_pk_bf16_f32 v13, v54, v55
	ds_write2_b64 v0, v[12:13], v[2:3] offset0:68 offset1:102
	global_store_dwordx2 v221, v[12:13], s[92:93] offset:16
	global_store_dwordx2 v221, v[2:3], s[92:93] offset:24
	v_cvt_pk_bf16_f32 v2, v10, v11
	v_cvt_pk_bf16_f32 v3, v14, v15
	ds_write2_b64 v0, v[2:3], v[6:7] offset0:136 offset1:170
	global_store_dwordx2 v221, v[2:3], s[92:93] offset:32
	global_store_dwordx2 v221, v[6:7], s[92:93] offset:40
	v_cvt_pk_bf16_f32 v2, v44, v45
	v_cvt_pk_bf16_f32 v3, v26, v27
	v_cvt_pk_bf16_f32 v6, v8, v9
	v_cvt_pk_bf16_f32 v7, v4, v5
	ds_write2_b64 v0, v[2:3], v[6:7] offset0:204 offset1:238
	global_store_dwordx2 v221, v[2:3], s[92:93] offset:48
	global_store_dwordx2 v221, v[6:7], s[92:93] offset:56
	v_mov_b32_e32 v2, s2
	v_readlane_b32 s2, v254, 38
	v_mad_u32_u24 v66, v166, s56, v2
	v_and_b32_e32 v0, 48, v165
	v_mov_b32_e32 v2, s2
	v_mad_u32_u24 v67, v166, s56, v2
	v_mov_b32_e32 v2, 0
	s_movk_i32 s2, 0xffe0
	v_mov_b32_e32 v3, v2
	v_mov_b32_e32 v4, v2
	v_mov_b32_e32 v5, v2
	v_mov_b32_e32 v6, v2
	v_mov_b32_e32 v7, v2
	v_mov_b32_e32 v8, v2
	v_mov_b32_e32 v9, v2
	v_mov_b32_e32 v10, v2
	v_mov_b32_e32 v11, v2
	v_mov_b32_e32 v12, v2
	v_mov_b32_e32 v13, v2
	v_mov_b32_e32 v14, v2
	v_mov_b32_e32 v15, v2
	v_mov_b32_e32 v16, v2
	v_mov_b32_e32 v17, v2
	v_mov_b32_e32 v18, v2
	v_mov_b32_e32 v19, v2
	v_mov_b32_e32 v20, v2
	v_mov_b32_e32 v21, v2
	v_mov_b32_e32 v22, v2
	v_mov_b32_e32 v23, v2
	v_mov_b32_e32 v24, v2
	v_mov_b32_e32 v25, v2
	v_mov_b32_e32 v26, v2
	v_mov_b32_e32 v27, v2
	v_mov_b32_e32 v28, v2
	v_mov_b32_e32 v29, v2
	v_mov_b32_e32 v30, v2
	v_mov_b32_e32 v31, v2
	v_mov_b32_e32 v32, v2
	v_mov_b32_e32 v33, v2
	v_mov_b32_e32 v34, v2
	v_mov_b32_e32 v35, v2
	v_mov_b32_e32 v36, v2
	v_mov_b32_e32 v37, v2
	v_mov_b32_e32 v38, v2
	v_mov_b32_e32 v39, v2
	v_mov_b32_e32 v40, v2
	v_mov_b32_e32 v41, v2
	v_mov_b32_e32 v42, v2
	v_mov_b32_e32 v43, v2
	v_mov_b32_e32 v44, v2
	v_mov_b32_e32 v45, v2
	v_mov_b32_e32 v46, v2
	v_mov_b32_e32 v47, v2
	v_mov_b32_e32 v48, v2
	v_mov_b32_e32 v49, v2
	v_mov_b32_e32 v50, v2
	v_mov_b32_e32 v51, v2
	v_mov_b32_e32 v52, v2
	v_mov_b32_e32 v53, v2
	v_mov_b32_e32 v54, v2
	v_mov_b32_e32 v55, v2
	v_mov_b32_e32 v56, v2
	v_mov_b32_e32 v57, v2
	v_mov_b32_e32 v58, v2
	v_mov_b32_e32 v59, v2
	v_mov_b32_e32 v60, v2
	v_mov_b32_e32 v61, v2
	v_mov_b32_e32 v62, v2
	v_mov_b32_e32 v63, v2
	v_mov_b32_e32 v64, v2
	v_mov_b32_e32 v65, v2
	s_waitcnt lgkmcnt(0)
	s_barrier

; #define LAS __attribute__((address_space(3)))
; DI u32x4 pack8(const float (&v)[8]) { u32x4 w; w.x = pk2(v[0], v[1]); w.y = pk2(v[2], v[3]); w.z = pk2(v[4], v[5]); w.w = pk2(v[6], v[7]); return w; }
; template <int MI, int NI>
; DI void wgemm(f32x4 (&acc)[MI][NI], const LAS bf16_t* A, int pa, const LAS bf16_t* Bt, int pb, int K, int lane) {
;     const int r = lane & 15, q = lane >> 4;
;     const LAS bf16_t* ap = A + r * pa + q * 8; const LAS bf16_t* bp = Bt + r * pb + q * 8;
; #pragma unroll 1
;     for (int k = 0; k < K; k += 32) {
;         bf16x8 a[MI], b[NI];
; #pragma unroll
;         for (int mi = 0; mi < MI; ++mi) a[mi] = *(const LAS bf16x8*)(ap + mi * 16 * pa + k);
; #pragma unroll
;         for (int ni = 0; ni < NI; ++ni) b[ni] = *(const LAS bf16x8*)(bp + ni * 16 * pb + k);
; #pragma unroll
;         for (int mi = 0; mi < MI; ++mi)
; #pragma unroll
;             for (int ni = 0; ni < NI; ++ni) acc[mi][ni] = __builtin_amdgcn_mfma_f32_16x16x32_bf16(a[mi], b[ni], acc[mi][ni], 0, 0, 0);
;     }
; DI void ssd_pass2(LAS unsigned char* lds, const Args& a, const LayerP& P, int unit, int wv) {
;     ...
;         u32x4 rawB[7]; conv_load(Hb + C_XBC + 256 + g * 128 + cv * 8, c * 128 + t0, rawB);
;         __syncthreads();
;         f32x4 acc[4][2]; zero_acc(acc);
;         wgemm<4, 2>(acc, R1 + hh * 64 * PT, PT, Cm + lr * PT, PT, 128, lane);
; #pragma unroll
;         for (int ni = 0; ni < 2; ++ni) { const float e = __expf(acs[hh * 128 + lr + ni * 16 + r]);
; #pragma unroll
;             for (int mi = 0; mi < 4; ++mi) acc[mi][ni] = acc[mi][ni] * e; }
;         __syncthreads();
;         { float o[4][8]; conv_compute<true>(rawB, P.ssd_cw + 256 + g * 128 + cv * 8, 768, P.ssd_cb + 256 + g * 128 + cv * 8, o);
; #pragma unroll
;           for (int t = 0; t < 4; ++t) *(LAS u32x4*)(R1 + (t0 + t) * PT + cv * 8) = pack8(o[t]); }
;         u32x4 rawX[7]; conv_load(Hb + C_XBC + g * 128 + cv * 8, c * 128 + t0, rawX);
.LBB0_1401:
	s_or_b64 exec, exec, s[2:3]
	v_lshl_or_b32 v158, s77, 6, v119
	v_lshlrev_b32_e32 v158, 6, v158
	s_lshl_b32 s32, s34, 1
	s_add_i32 s32, s32, s15
	s_lshl_b32 s32, s32, 15
	v_add_u32_e32 v158, s32, v158
	s_add_u32 s98, s38, 0x1b100000
	s_addc_u32 s99, s39, 0
	global_load_dwordx4 v[168:171], v158, s[98:99]
	global_load_dwordx4 v[172:175], v158, s[98:99] offset:16
	global_load_dwordx4 v[176:179], v158, s[98:99] offset:32
	global_load_dwordx4 v[180:183], v158, s[98:99] offset:48
	v_lshl_add_u64 v[108:109], s[94:95], 0, v[0:1]
	v_and_b32_e32 v0, 48, v119
	v_mad_u32_u24 v124, v120, s56, v0
	v_add_u32_e32 v123, s68, v124
	v_add_u32_e32 v0, s69, v124
	v_mov_b32_e32 v2, 0
	s_xor_b64 s[36:37], s[50:51], -1
	s_movk_i32 s2, 0xffe0
	v_mov_b32_e32 v62, v0
	v_mov_b32_e32 v63, v123
	v_mov_b32_e32 v3, v2
	v_mov_b32_e32 v4, v2
	v_mov_b32_e32 v5, v2
	v_mov_b32_e32 v10, v2
	v_mov_b32_e32 v11, v2
	v_mov_b32_e32 v12, v2
	v_mov_b32_e32 v13, v2
	v_mov_b32_e32 v6, v2
	v_mov_b32_e32 v7, v2
	v_mov_b32_e32 v8, v2
	v_mov_b32_e32 v9, v2
	v_mov_b32_e32 v18, v2
	v_mov_b32_e32 v19, v2
	v_mov_b32_e32 v20, v2
	v_mov_b32_e32 v21, v2
	v_mov_b32_e32 v14, v2
	v_mov_b32_e32 v15, v2
	v_mov_b32_e32 v16, v2
	v_mov_b32_e32 v17, v2
	v_mov_b32_e32 v26, v2
	v_mov_b32_e32 v27, v2
	v_mov_b32_e32 v28, v2
	v_mov_b32_e32 v29, v2
	v_mov_b32_e32 v22, v2
	v_mov_b32_e32 v23, v2
	v_mov_b32_e32 v24, v2
	v_mov_b32_e32 v25, v2
	v_mov_b32_e32 v30, v2
	v_mov_b32_e32 v31, v2
	v_mov_b32_e32 v32, v2
	v_mov_b32_e32 v33, v2
	s_waitcnt lgkmcnt(0)
	s_barrier
.LBB0_1402:
	ds_read_b128 v[64:67], v63
	ds_read_b128 v[68:71], v62
	ds_read_b128 v[72:75], v62 offset:4352
	s_add_i32 s2, s2, 32
	s_cmpk_lt_u32 s2, 0x60
	v_add_u32_e32 v62, 64, v62
	s_waitcnt lgkmcnt(1)
	v_mfma_f32_16x16x32_bf16 v[30:33], v[64:67], v[68:71], v[30:33]
	s_waitcnt lgkmcnt(0)
	v_mfma_f32_16x16x32_bf16 v[22:25], v[64:67], v[72:75], v[22:25]
	ds_read_b128 v[64:67], v63 offset:4352
	s_waitcnt lgkmcnt(0)
	v_mfma_f32_16x16x32_bf16 v[26:29], v[64:67], v[68:71], v[26:29]
	v_mfma_f32_16x16x32_bf16 v[14:17], v[64:67], v[72:75], v[14:17]
	ds_read_b128 v[64:67], v63 offset:8704
	s_waitcnt lgkmcnt(0)
	v_mfma_f32_16x16x32_bf16 v[18:21], v[64:67], v[68:71], v[18:21]
	v_mfma_f32_16x16x32_bf16 v[6:9], v[64:67], v[72:75], v[6:9]
	ds_read_b128 v[64:67], v63 offset:13056
	v_add_u32_e32 v63, 64, v63
	s_waitcnt lgkmcnt(0)
	v_mfma_f32_16x16x32_bf16 v[10:13], v[64:67], v[68:71], v[10:13]
	v_mfma_f32_16x16x32_bf16 v[2:5], v[64:67], v[72:75], v[2:5]
	s_cbranch_scc1 .LBB0_1402
	v_readlane_b32 s2, v254, 13
	v_add_co_u32_e32 v72, vcc, 0x1000, v102
	s_nop 0
	v_lshl_add_u32 v62, v120, 2, s2
	s_mov_b64 s[2:3], 0x400
	v_lshl_add_u64 v[70:71], v[102:103], 0, s[2:3]
	s_mov_b64 s[2:3], 0x1c00
	ds_read2_b32 v[110:111], v62 offset1:16
	s_waitcnt lgkmcnt(0)
	s_barrier
	s_waitcnt vmcnt(0)
	s_mov_b32 s32, 0x05040100
	s_mov_b32 s98, 0x07060302
	v_perm_b32 v220, v170, v168, s32
	v_perm_b32 v221, v174, v172, s32
	v_perm_b32 v222, v178, v176, s32
	v_perm_b32 v223, v182, v180, s32
	v_perm_b32 v224, v170, v168, s98
	v_perm_b32 v225, v174, v172, s98
	v_perm_b32 v226, v178, v176, s98
	v_perm_b32 v227, v182, v180, s98
	v_perm_b32 v228, v171, v169, s32
	v_perm_b32 v229, v175, v173, s32
	v_perm_b32 v230, v179, v177, s32
	v_perm_b32 v231, v183, v181, s32
	v_perm_b32 v232, v171, v169, s98
	v_perm_b32 v233, v175, v173, s98
	v_perm_b32 v234, v179, v177, s98
	v_perm_b32 v235, v183, v181, s98
	ds_write_b128 v132, v[220:223] offset:34816
	ds_write_b128 v132, v[224:227] offset:35088
	ds_write_b128 v132, v[228:231] offset:35360
	ds_write_b128 v133, v[232:235] offset:34816
	v_mov_b32_e32 v38, 0
	v_mov_b32_e32 v34, 0
	v_mov_b32_e32 v35, 0
	v_mov_b32_e32 v36, 0
	v_mov_b32_e32 v37, 0
	s_and_saveexec_b64 s[2:3], s[16:17]
	s_cbranch_execz .LBB0_1405
	v_mad_u64_u32 v[34:35], s[16:17], v126, s73, v[106:107]
	global_load_dwordx4 v[34:37], v[34:35], off offset:1312
